# nt (streaming) policy also on the gate phase's once-read row loads and on the final norm's loads and output stores
# speedup vs baseline: 1.0140x; 1.0027x over previous
; __device__ __forceinline__ float bflo(unsigned w) { return __uint_as_float(w << 16); }
; __device__ __forceinline__ float bfhi(unsigned w) { return __uint_as_float(w & 0xffff0000u); }
; __global__ void __launch_bounds__(512, 2) mk_fwd(Params p) {
;     ...
;             for (int m = gw; m < M; m += NGW) {
;                 f32x4* xr = (f32x4*)(p.out + (size_t)m * DM) + lane; const f32x4* wr_ = (const f32x4*)p.fnorm + lane; const v2u* xb8 = (const v2u*)(XB + (size_t)m * DM) + lane;
;                 const float rstd = 1.0f / sqrtf(wave_sum(lane < 32 ? ROWSQ[((size_t)DEPTH * M + m) * 32 + lane] : 0.f) * (1.0f / DM) + EPS);
; #pragma unroll
;                 for (int j = 0; j < 8; ++j) { const v2u w = xb8[64 * j]; const f32x4 v = {bflo(w.x), bfhi(w.x), bflo(w.y), bfhi(w.y)}; xr[64 * j] = v * rstd * wr_[64 * j]; }
;             }
.LBB0_26:
	s_or_b64 exec, exec, s[0:1]
	global_load_dwordx2 v[28:29], v[16:17], off offset:-2048 nt
	global_load_dwordx4 v[24:27], v[2:3], off
	s_waitcnt vmcnt(0)
	ds_bpermute_b32 v30, v18, v0
	s_add_i32 s4, s4, s26
	v_lshl_add_u64 v[12:13], v[12:13], 0, s[16:17]
	s_cmpk_gt_i32 s4, 0x3fff
	s_waitcnt lgkmcnt(0)
	v_add_f32_e32 v0, v0, v30
	ds_bpermute_b32 v30, v19, v0
	s_waitcnt lgkmcnt(0)
	v_add_f32_e32 v0, v0, v30
	ds_bpermute_b32 v30, v20, v0
	s_waitcnt lgkmcnt(0)
	v_add_f32_e32 v0, v0, v30
	ds_bpermute_b32 v30, v21, v0
	s_waitcnt lgkmcnt(0)
	v_add_f32_e32 v0, v0, v30
	ds_bpermute_b32 v30, v22, v0
	s_waitcnt lgkmcnt(0)
	v_add_f32_e32 v0, v0, v30
	ds_bpermute_b32 v30, v23, v0
	s_waitcnt lgkmcnt(0)
	v_add_f32_e32 v0, v0, v30
	v_fmamk_f32 v0, v0, 0x3a000000, v215
	v_mul_f32_e32 v30, 0x4f800000, v0
	v_cmp_gt_f32_e32 vcc, s33, v0
	s_nop 1
	v_cndmask_b32_e32 v0, v0, v30, vcc
	v_sqrt_f32_e32 v30, v0
	s_nop 0
	v_add_u32_e32 v31, -1, v30
	v_add_u32_e32 v32, 1, v30
	v_fma_f32 v33, -v31, v30, v0
	v_fma_f32 v34, -v32, v30, v0
	v_cmp_ge_f32_e64 s[0:1], 0, v33
	s_nop 1
	v_cndmask_b32_e64 v30, v30, v31, s[0:1]
	v_cmp_lt_f32_e64 s[0:1], 0, v34
	s_nop 1
	v_cndmask_b32_e64 v30, v30, v32, s[0:1]
	v_mul_f32_e32 v31, 0x37800000, v30
	v_cndmask_b32_e32 v30, v30, v31, vcc
	v_cmp_class_f32_e32 vcc, v0, v216
	s_nop 1
	v_cndmask_b32_e32 v0, v30, v0, vcc
	v_div_scale_f32 v32, s[0:1], v0, v0, 1.0
	v_rcp_f32_e32 v33, v32
	s_movk_i32 s0, 0xf000
	v_add_co_u32_e32 v30, vcc, s0, v14
	v_fma_f32 v35, -v32, v33, 1.0
	s_nop 0
	v_addc_co_u32_e32 v31, vcc, -1, v15, vcc
	v_div_scale_f32 v34, vcc, 1.0, v0, 1.0
	v_fmac_f32_e32 v33, v35, v33
	v_mul_f32_e32 v35, v34, v33
	v_fma_f32 v36, -v32, v35, v34
	v_fmac_f32_e32 v35, v36, v33
	v_fma_f32 v32, -v32, v35, v34
	v_div_fmas_f32 v32, v32, v33, v35
	v_div_fixup_f32 v0, v32, v0, 1.0
	s_waitcnt vmcnt(1)
	v_lshlrev_b32_e32 v32, 16, v28
	v_and_b32_e32 v33, 0xffff0000, v28
	v_lshlrev_b32_e32 v28, 16, v29
	v_and_b32_e32 v29, 0xffff0000, v29
	v_pk_mul_f32 v[32:33], v[0:1], v[32:33] op_sel_hi:[0,1]
	v_pk_mul_f32 v[28:29], v[0:1], v[28:29] op_sel_hi:[0,1]
	s_waitcnt vmcnt(0)
	v_pk_mul_f32 v[26:27], v[26:27], v[28:29]
	v_pk_mul_f32 v[24:25], v[24:25], v[32:33]
	global_store_dwordx4 v[30:31], v[24:27], off offset:-3072 nt
	global_load_dwordx2 v[28:29], v[16:17], off offset:-1536 nt
	s_nop 0
	global_load_dwordx4 v[24:27], v[2:3], off offset:1024
	s_waitcnt vmcnt(1)
	v_lshlrev_b32_e32 v32, 16, v28
	v_and_b32_e32 v33, 0xffff0000, v28
	v_lshlrev_b32_e32 v28, 16, v29
	v_and_b32_e32 v29, 0xffff0000, v29
	v_pk_mul_f32 v[32:33], v[0:1], v[32:33] op_sel_hi:[0,1]
	v_pk_mul_f32 v[28:29], v[0:1], v[28:29] op_sel_hi:[0,1]
	s_waitcnt vmcnt(0)
	v_pk_mul_f32 v[26:27], v[26:27], v[28:29]
	v_pk_mul_f32 v[24:25], v[24:25], v[32:33]
	global_store_dwordx4 v[30:31], v[24:27], off offset:-2048 nt
	global_load_dwordx2 v[28:29], v[16:17], off offset:-1024 nt
	s_nop 0
	global_load_dwordx4 v[24:27], v[2:3], off offset:2048
	s_waitcnt vmcnt(1)
	v_lshlrev_b32_e32 v32, 16, v28
	v_and_b32_e32 v33, 0xffff0000, v28
	v_lshlrev_b32_e32 v28, 16, v29
	v_and_b32_e32 v29, 0xffff0000, v29
	v_pk_mul_f32 v[32:33], v[0:1], v[32:33] op_sel_hi:[0,1]
	v_pk_mul_f32 v[28:29], v[0:1], v[28:29] op_sel_hi:[0,1]
	s_waitcnt vmcnt(0)
	v_pk_mul_f32 v[26:27], v[26:27], v[28:29]
	v_pk_mul_f32 v[24:25], v[24:25], v[32:33]
	global_store_dwordx4 v[30:31], v[24:27], off offset:-1024 nt
	global_load_dwordx2 v[28:29], v[16:17], off offset:-512 nt
	s_nop 0
	global_load_dwordx4 v[24:27], v[2:3], off offset:3072
	s_waitcnt vmcnt(1)
	v_lshlrev_b32_e32 v30, 16, v28
	v_and_b32_e32 v31, 0xffff0000, v28
	v_lshlrev_b32_e32 v28, 16, v29
	v_and_b32_e32 v29, 0xffff0000, v29
	v_pk_mul_f32 v[30:31], v[0:1], v[30:31] op_sel_hi:[0,1]
	v_pk_mul_f32 v[28:29], v[0:1], v[28:29] op_sel_hi:[0,1]
	s_waitcnt vmcnt(0)
	v_pk_mul_f32 v[26:27], v[26:27], v[28:29]
	v_pk_mul_f32 v[24:25], v[24:25], v[30:31]
	global_store_dwordx4 v[14:15], v[24:27], off offset:-4096 nt
	global_load_dwordx2 v[28:29], v[16:17], off nt
	s_nop 0
	global_load_dwordx4 v[24:27], v[4:5], off
	s_waitcnt vmcnt(1)
	v_lshlrev_b32_e32 v30, 16, v28
	v_and_b32_e32 v31, 0xffff0000, v28
	v_lshlrev_b32_e32 v28, 16, v29
	v_and_b32_e32 v29, 0xffff0000, v29
	v_pk_mul_f32 v[30:31], v[0:1], v[30:31] op_sel_hi:[0,1]
	v_pk_mul_f32 v[28:29], v[0:1], v[28:29] op_sel_hi:[0,1]
	s_waitcnt vmcnt(0)
	v_pk_mul_f32 v[26:27], v[26:27], v[28:29]
	v_pk_mul_f32 v[24:25], v[24:25], v[30:31]
	global_store_dwordx4 v[14:15], v[24:27], off offset:-3072 nt
	global_load_dwordx2 v[28:29], v[16:17], off offset:512 nt
	s_nop 0
	global_load_dwordx4 v[24:27], v[6:7], off
	s_waitcnt vmcnt(1)
	v_lshlrev_b32_e32 v30, 16, v28
	v_and_b32_e32 v31, 0xffff0000, v28
	v_lshlrev_b32_e32 v28, 16, v29
	v_and_b32_e32 v29, 0xffff0000, v29
	v_pk_mul_f32 v[30:31], v[0:1], v[30:31] op_sel_hi:[0,1]
	v_pk_mul_f32 v[28:29], v[0:1], v[28:29] op_sel_hi:[0,1]
	s_waitcnt vmcnt(0)
	v_pk_mul_f32 v[26:27], v[26:27], v[28:29]
	v_pk_mul_f32 v[24:25], v[24:25], v[30:31]
	global_store_dwordx4 v[14:15], v[24:27], off offset:-2048 nt
	global_load_dwordx2 v[28:29], v[16:17], off offset:1024 nt
	s_nop 0
	global_load_dwordx4 v[24:27], v[8:9], off
	s_waitcnt vmcnt(1)
	v_lshlrev_b32_e32 v30, 16, v28
	v_and_b32_e32 v31, 0xffff0000, v28
	v_lshlrev_b32_e32 v28, 16, v29
	v_and_b32_e32 v29, 0xffff0000, v29
	v_pk_mul_f32 v[30:31], v[0:1], v[30:31] op_sel_hi:[0,1]
	v_pk_mul_f32 v[28:29], v[0:1], v[28:29] op_sel_hi:[0,1]
	s_waitcnt vmcnt(0)
	v_pk_mul_f32 v[26:27], v[26:27], v[28:29]
	v_pk_mul_f32 v[24:25], v[24:25], v[30:31]
	global_store_dwordx4 v[14:15], v[24:27], off offset:-1024 nt
	global_load_dwordx2 v[28:29], v[16:17], off offset:1536 nt
	s_nop 0
	global_load_dwordx4 v[24:27], v[10:11], off
	v_lshl_add_u64 v[16:17], v[16:17], 0, s[20:21]
	s_waitcnt vmcnt(1)
	v_lshlrev_b32_e32 v30, 16, v28
	v_and_b32_e32 v31, 0xffff0000, v28
	v_lshlrev_b32_e32 v28, 16, v29
	v_and_b32_e32 v29, 0xffff0000, v29
	v_pk_mul_f32 v[30:31], v[0:1], v[30:31] op_sel_hi:[0,1]
	v_pk_mul_f32 v[28:29], v[0:1], v[28:29] op_sel_hi:[0,1]
	s_waitcnt vmcnt(0)
	v_pk_mul_f32 v[26:27], v[26:27], v[28:29]
	v_pk_mul_f32 v[24:25], v[24:25], v[30:31]
	global_store_dwordx4 v[14:15], v[24:27], off nt
	v_lshl_add_u64 v[14:15], v[14:15], 0, s[18:19]
	s_cbranch_scc1 .LBB0_32

; __device__ __forceinline__ void gate_row(int m, int lane, const bf16_t* __restrict__ YA, const bf16_t* __restrict__ YB, const float* __restrict__ LSE, const bf16_t* __restrict__ PROJ, ...
;     v4u a[2], b0[2], b1[2], b2[2], ga[2], gb[2]; float l0[2], l1[2], l2[2];
; #pragma unroll
;     for (int j = 0; j < 2; ++j) { const int c = lane + 64 * j, hh = c >> 4;
;         a[j] = *(const v4u*)(YA + (size_t)m * DA + 8 * c);
;         b0[j] = *(const v4u*)(YB + ((size_t)0 * M + m) * DB + 8 * c); b1[j] = *(const v4u*)(YB + ((size_t)1 * M + m) * DB + 8 * c); b2[j] = *(const v4u*)(YB + ((size_t)2 * M + m) * DB + 8 * c);
;         l0[j] = LSE[((size_t)0 * M + m) * 8 + hh]; l1[j] = LSE[((size_t)1 * M + m) * 8 + hh]; l2[j] = LSE[((size_t)2 * M + m) * 8 + hh];
;         ga[j] = *(const v4u*)(PROJ + ((size_t)(H_GA + (c >> 4)) * M + m) * HD + 8 * (c & 15)); gb[j] = *(const v4u*)(PROJ + ((size_t)(H_GB + (c >> 4)) * M + m) * HD + 8 * (c & 15)); }
;     float ya[2][8], yb[2][8]; float ssa = 0.f, ssb = 0.f;
; #pragma unroll
;     for (int j = 0; j < 2; ++j) {
;         ya[j][0] = bflo(a[j].x); ya[j][1] = bfhi(a[j].x); ya[j][2] = bflo(a[j].y); ya[j][3] = bfhi(a[j].y); ya[j][4] = bflo(a[j].z); ya[j][5] = bfhi(a[j].z); ya[j][6] = bflo(a[j].w); ya[j][7] = bfhi(a[j].w);
;         const float mx = fmaxf(l0[j], fmaxf(l1[j], l2[j])); const float e0 = __builtin_amdgcn_exp2f(l0[j] - mx), e1 = __builtin_amdgcn_exp2f(l1[j] - mx), e2 = __builtin_amdgcn_exp2f(l2[j] - mx);
;         const float inv = __builtin_amdgcn_rcpf(e0 + e1 + e2); const float w0 = e0 * inv, w1 = e1 * inv, w2 = e2 * inv;
;         yb[j][0] = w0 * bflo(b0[j].x) + w1 * bflo(b1[j].x) + w2 * bflo(b2[j].x); yb[j][1] = w0 * bfhi(b0[j].x) + w1 * bfhi(b1[j].x) + w2 * bfhi(b2[j].x);
;         yb[j][2] = w0 * bflo(b0[j].y) + w1 * bflo(b1[j].y) + w2 * bflo(b2[j].y); yb[j][3] = w0 * bfhi(b0[j].y) + w1 * bfhi(b1[j].y) + w2 * bfhi(b2[j].y);
;         yb[j][4] = w0 * bflo(b0[j].z) + w1 * bflo(b1[j].z) + w2 * bflo(b2[j].z); yb[j][5] = w0 * bfhi(b0[j].z) + w1 * bfhi(b1[j].z) + w2 * bfhi(b2[j].z);
;         yb[j][6] = w0 * bflo(b0[j].w) + w1 * bflo(b1[j].w) + w2 * bflo(b2[j].w); yb[j][7] = w0 * bfhi(b0[j].w) + w1 * bfhi(b1[j].w) + w2 * bfhi(b2[j].w);
; #pragma unroll
;         for (int i = 0; i < 8; ++i) { ssa += ya[j][i] * ya[j][i]; ssb += yb[j][i] * yb[j][i]; } }
.LBB0_41:
	v_lshl_add_u64 v[2:3], v[64:65], 0, s[28:29]
	v_add_co_u32_e32 v4, vcc, 0x19800000, v2
	s_mov_b32 s0, 0x21800000
	s_nop 0
	v_addc_co_u32_e32 v5, vcc, 0, v3, vcc
	v_add_co_u32_e32 v6, vcc, 0x1b800000, v2
	global_load_dwordx4 v[10:13], v[4:5], off nt
	s_nop 0
	v_addc_co_u32_e32 v7, vcc, 0, v3, vcc
	v_add_co_u32_e32 v8, vcc, 0x1d800000, v2
	global_load_dwordx4 v[38:41], v[6:7], off nt
	s_nop 0
	v_addc_co_u32_e32 v9, vcc, 0, v3, vcc
	v_add_co_u32_e32 v26, vcc, 0x1f800000, v2
	global_load_dwordx4 v[42:45], v[8:9], off nt
	s_nop 0
	v_addc_co_u32_e32 v27, vcc, 0, v3, vcc
	v_lshl_add_u64 v[2:3], v[72:73], 0, s[28:29]
	v_add_co_u32_e32 v14, vcc, 0x21800000, v2
	global_load_dwordx4 v[46:49], v[26:27], off nt
	s_nop 0
	v_addc_co_u32_e32 v15, vcc, 0, v3, vcc
	global_load_dword v76, v[14:15], off nt
	v_add_co_u32_e32 v14, vcc, 0x21880000, v2
	s_add_i32 s44, s26, s3
	s_nop 0
	v_addc_co_u32_e32 v15, vcc, 0, v3, vcc
	v_add_co_u32_e32 v2, vcc, 0x21900000, v2
	global_load_dword v78, v[14:15], off nt
	s_nop 0
	v_addc_co_u32_e32 v3, vcc, 0, v3, vcc
	global_load_dword v79, v[2:3], off nt
	v_lshl_add_u64 v[2:3], v[70:71], 0, s[28:29]
	v_add_co_u32_e32 v14, vcc, s33, v2
	s_cmpk_gt_i32 s44, 0x3fff
	s_nop 0
	v_addc_co_u32_e32 v15, vcc, 0, v3, vcc
	v_add_co_u32_e32 v2, vcc, 0x17800000, v2
	global_load_dwordx4 v[22:25], v[14:15], off nt
	s_nop 0
	v_addc_co_u32_e32 v3, vcc, 0, v3, vcc
	global_load_dwordx4 v[14:17], v[2:3], off nt
	s_nop 0
	global_load_dwordx4 v[2:5], v[4:5], off offset:1024 nt
	s_nop 0
	global_load_dwordx4 v[18:21], v[6:7], off offset:1024 nt
	global_load_dwordx4 v[34:37], v[8:9], off offset:1024 nt
	global_load_dwordx4 v[30:33], v[26:27], off offset:1024 nt
	v_lshl_add_u64 v[6:7], v[74:75], 0, s[28:29]
	v_add_co_u32_e32 v8, vcc, s0, v6
	s_mov_b32 s0, 0x21880000
	s_nop 0
	v_addc_co_u32_e32 v9, vcc, 0, v7, vcc
	global_load_dword v82, v[8:9], off nt
	v_add_co_u32_e32 v8, vcc, s0, v6
	s_mov_b32 s0, 0x21900000
	s_nop 0
	v_addc_co_u32_e32 v9, vcc, 0, v7, vcc
	v_add_co_u32_e32 v6, vcc, s0, v6
	global_load_dword v83, v[8:9], off nt
	s_nop 0
	v_addc_co_u32_e32 v7, vcc, 0, v7, vcc
	global_load_dword v87, v[6:7], off nt
	v_lshl_add_u64 v[26:27], v[68:69], 0, s[28:29]
	v_add_co_u32_e32 v6, vcc, s33, v26
	s_mov_b32 s0, 0x17800000
	s_nop 0
	v_addc_co_u32_e32 v7, vcc, 0, v27, vcc
	v_add_co_u32_e32 v26, vcc, s0, v26
	global_load_dwordx4 v[6:9], v[6:7], off nt
	s_nop 0
	v_addc_co_u32_e32 v27, vcc, 0, v27, vcc
	global_load_dwordx4 v[26:29], v[26:27], off nt
	s_waitcnt vmcnt(0)
	v_and_b32_e32 v93, 0xffff0000, v13
	v_lshlrev_b32_e32 v131, 16, v10
	v_and_b32_e32 v133, 0xffff0000, v10
	v_lshlrev_b32_e32 v109, 16, v11
	v_and_b32_e32 v123, 0xffff0000, v11
	v_lshlrev_b32_e32 v103, 16, v12
	s_waitcnt vmcnt(15)
	v_lshlrev_b32_e32 v84, 16, v43
	v_and_b32_e32 v85, 0xffff0000, v43
	v_lshlrev_b32_e32 v89, 16, v44
	v_and_b32_e32 v44, 0xffff0000, v44
	v_lshlrev_b32_e32 v90, 16, v45
	s_waitcnt vmcnt(11)
	v_max3_f32 v80, v76, v78, v79
	v_sub_f32_e32 v76, v76, v80
	v_exp_f32_e32 v77, v76
	v_sub_f32_e32 v76, v78, v80
	v_exp_f32_e32 v81, v76
	v_sub_f32_e32 v76, v79, v80
	v_exp_f32_e32 v76, v76
	v_lshlrev_b32_e32 v79, 16, v42
	v_add_f32_e32 v78, v77, v81
	v_and_b32_e32 v80, 0xffff0000, v42
	v_add_f32_e32 v78, v76, v78
	v_rcp_f32_e32 v78, v78
	s_waitcnt vmcnt(8)
	v_lshlrev_b32_e32 v111, 16, v3
	v_and_b32_e32 v119, 0xffff0000, v3
	v_lshlrev_b32_e32 v129, 16, v2
	v_pk_mul_f32 v[42:43], v[76:77], v[78:79] op_sel_hi:[1,0]
	v_lshlrev_b32_e32 v77, 16, v38
	v_lshlrev_b32_e32 v76, 16, v46
	v_mul_f32_e32 v88, v81, v78
	v_pk_mul_f32 v[76:77], v[42:43], v[76:77]
	v_and_b32_e32 v78, 0xffff0000, v46
	v_fma_f32 v77, v88, v79, v77
	v_and_b32_e32 v79, 0xffff0000, v38
	v_pk_mul_f32 v[78:79], v[42:43], v[78:79]
	v_lshlrev_b32_e32 v81, 16, v39
	v_fma_f32 v38, v88, v80, v79
	v_lshlrev_b32_e32 v80, 16, v47
	v_pk_mul_f32 v[80:81], v[42:43], v[80:81]
	v_add_f32_e32 v79, v78, v38
	v_fma_f32 v38, v88, v84, v81
	v_add_f32_e32 v86, v80, v38
	v_and_b32_e32 v39, 0xffff0000, v39
	v_and_b32_e32 v38, 0xffff0000, v47
	v_pk_mul_f32 v[38:39], v[42:43], v[38:39]
	s_waitcnt vmcnt(6)
	v_lshlrev_b32_e32 v46, 16, v35
	v_fma_f32 v39, v88, v85, v39
	v_add_f32_e32 v85, v38, v39
	v_lshlrev_b32_e32 v39, 16, v40
	v_lshlrev_b32_e32 v38, 16, v48
	v_pk_mul_f32 v[38:39], v[42:43], v[38:39]
	v_add_f32_e32 v77, v76, v77
	v_fma_f32 v39, v88, v89, v39
	v_add_f32_e32 v84, v38, v39
	v_and_b32_e32 v39, 0xffff0000, v40
	v_and_b32_e32 v38, 0xffff0000, v48
	v_pk_mul_f32 v[38:39], v[42:43], v[38:39]
	v_and_b32_e32 v40, 0xffff0000, v45
	v_fma_f32 v39, v88, v44, v39
	v_add_f32_e32 v47, v38, v39
	v_lshlrev_b32_e32 v39, 16, v41
	v_lshlrev_b32_e32 v38, 16, v49
	v_pk_mul_f32 v[38:39], v[42:43], v[38:39]
	v_lshlrev_b32_e32 v44, 16, v34
	v_fma_f32 v39, v88, v90, v39
	v_add_f32_e32 v92, v38, v39
	v_and_b32_e32 v39, 0xffff0000, v41
	v_and_b32_e32 v38, 0xffff0000, v49
	v_pk_mul_f32 v[38:39], v[42:43], v[38:39]
	v_and_b32_e32 v45, 0xffff0000, v34
	v_fma_f32 v39, v88, v40, v39
	v_add_f32_e32 v43, v38, v39
	s_waitcnt vmcnt(2)
; __device__ __forceinline__ void gate_row(int m, int lane, const bf16_t* __restrict__ YA, const bf16_t* __restrict__ YB, const float* __restrict__ LSE, const bf16_t* __restrict__ PROJ, ...
;     ...
;         const float mx = fmaxf(l0[j], fmaxf(l1[j], l2[j])); const float e0 = __builtin_amdgcn_exp2f(l0[j] - mx), e1 = __builtin_amdgcn_exp2f(l1[j] - mx), e2 = __builtin_amdgcn_exp2f(l2[j] - mx);
;         const float inv = __builtin_amdgcn_rcpf(e0 + e1 + e2); const float w0 = e0 * inv, w1 = e1 * inv, w2 = e2 * inv;
;         yb[j][0] = w0 * bflo(b0[j].x) + w1 * bflo(b1[j].x) + w2 * bflo(b2[j].x); yb[j][1] = w0 * bfhi(b0[j].x) + w1 * bfhi(b1[j].x) + w2 * bfhi(b2[j].x);
;         yb[j][2] = w0 * bflo(b0[j].y) + w1 * bflo(b1[j].y) + w2 * bflo(b2[j].y); yb[j][3] = w0 * bfhi(b0[j].y) + w1 * bfhi(b1[j].y) + w2 * bfhi(b2[j].y);
;         yb[j][4] = w0 * bflo(b0[j].z) + w1 * bflo(b1[j].z) + w2 * bflo(b2[j].z); yb[j][5] = w0 * bfhi(b0[j].z) + w1 * bfhi(b1[j].z) + w2 * bfhi(b2[j].z);
;         yb[j][6] = w0 * bflo(b0[j].w) + w1 * bflo(b1[j].w) + w2 * bflo(b2[j].w); yb[j][7] = w0 * bfhi(b0[j].w) + w1 * bfhi(b1[j].w) + w2 * bfhi(b2[j].w);
; #pragma unroll
;         for (int i = 0; i < 8; ++i) { ssa += ya[j][i] * ya[j][i]; ssb += yb[j][i] * yb[j][i]; } }
;     const float ra = 1.0f / sqrtf(wave_sum(ssa) * (1.0f / DA) + EPS), rb = 1.0f / sqrtf(wave_sum(ssb) * (1.0f / DB) + EPS);
; #pragma unroll
;     for (int j = 0; j < 2; ++j) { const int c = lane + 64 * j;
;         const float gaf[8] = {bflo(ga[j].x), bfhi(ga[j].x), bflo(ga[j].y), bfhi(ga[j].y), bflo(ga[j].z), bfhi(ga[j].z), bflo(ga[j].w), bfhi(ga[j].w)};
;         const float gbf[8] = {bflo(gb[j].x), bfhi(gb[j].x), bflo(gb[j].y), bfhi(gb[j].y), bflo(gb[j].z), bfhi(gb[j].z), bflo(gb[j].w), bfhi(gb[j].w)};
;         const f32x4 wa0 = *(const f32x4*)(wa + 8 * c), wa1 = *(const f32x4*)(wa + 8 * c + 4), wb0 = *(const f32x4*)(wb + 8 * c), wb1 = *(const f32x4*)(wb + 8 * c + 4);
;         float za[8], zb[8];
; #pragma unroll
;         for (int i = 0; i < 8; ++i) { const float wai = i < 4 ? wa0[i & 3] : wa1[i & 3], wbi = i < 4 ? wb0[i & 3] : wb1[i & 3];
;             const float sa = gaf[i] * __builtin_amdgcn_rcpf(1.0f + __builtin_amdgcn_exp2f(-1.4426950408889634f * gaf[i])), sb = gbf[i] * __builtin_amdgcn_rcpf(1.0f + __builtin_amdgcn_exp2f(-1.4426950408889634f * gbf[i]));
	v_max3_f32 v38, v82, v83, v87
	v_sub_f32_e32 v39, v82, v38
	v_sub_f32_e32 v40, v83, v38
	v_exp_f32_e32 v39, v39
	v_exp_f32_e32 v41, v40
	v_sub_f32_e32 v38, v87, v38
	v_exp_f32_e32 v38, v38
	v_and_b32_e32 v48, 0xffff0000, v35
	v_add_f32_e32 v40, v39, v41
	v_mul_f32_e32 v42, v79, v79
	v_add_f32_e32 v40, v38, v40
	v_rcp_f32_e32 v40, v40
	v_fmac_f32_e32 v42, v77, v77
	v_fmac_f32_e32 v42, v86, v86
	v_fmac_f32_e32 v42, v85, v85
	v_mul_f32_e32 v41, v41, v40
	v_pk_mul_f32 v[34:35], v[38:39], v[40:41] op_sel_hi:[1,0]
	v_lshlrev_b32_e32 v39, 16, v18
	v_lshlrev_b32_e32 v38, 16, v30
	v_pk_mul_f32 v[38:39], v[34:35], v[38:39]
	v_lshlrev_b32_e32 v49, 16, v36
	v_fma_f32 v39, v41, v44, v39
	v_add_f32_e32 v87, v38, v39
	v_and_b32_e32 v39, 0xffff0000, v18
	v_and_b32_e32 v38, 0xffff0000, v30
	v_pk_mul_f32 v[38:39], v[34:35], v[38:39]
	v_fmac_f32_e32 v42, v84, v84
	v_fma_f32 v18, v41, v45, v39
	v_add_f32_e32 v99, v38, v18
	v_lshlrev_b32_e32 v39, 16, v19
	v_lshlrev_b32_e32 v38, 16, v31
	v_pk_mul_f32 v[38:39], v[34:35], v[38:39]
	v_and_b32_e32 v19, 0xffff0000, v19
	v_fma_f32 v18, v41, v46, v39
	v_add_f32_e32 v91, v38, v18
	v_and_b32_e32 v18, 0xffff0000, v31
	v_pk_mul_f32 v[18:19], v[34:35], v[18:19]
	v_fmac_f32_e32 v42, v47, v47
	v_fma_f32 v19, v41, v48, v19
	v_add_f32_e32 v90, v18, v19
	v_lshlrev_b32_e32 v19, 16, v20
	v_lshlrev_b32_e32 v18, 16, v32
	v_pk_mul_f32 v[18:19], v[34:35], v[18:19]
	v_fmac_f32_e32 v42, v92, v92
	v_fma_f32 v19, v41, v49, v19
	v_add_f32_e32 v88, v18, v19
	v_and_b32_e32 v19, 0xffff0000, v20
	v_and_b32_e32 v18, 0xffff0000, v32
	v_and_b32_e32 v36, 0xffff0000, v36
	v_pk_mul_f32 v[18:19], v[34:35], v[18:19]
	v_fmac_f32_e32 v42, v43, v43
	v_fma_f32 v19, v41, v36, v19
	v_add_f32_e32 v89, v18, v19
	v_lshlrev_b32_e32 v19, 16, v21
	v_lshlrev_b32_e32 v18, 16, v33
	v_fmac_f32_e32 v42, v87, v87
	v_lshlrev_b32_e32 v76, 16, v37
	v_pk_mul_f32 v[18:19], v[34:35], v[18:19]
	v_fmac_f32_e32 v42, v99, v99
	v_fma_f32 v19, v41, v76, v19
	v_fmac_f32_e32 v42, v91, v91
	v_add_f32_e32 v94, v18, v19
	v_and_b32_e32 v19, 0xffff0000, v21
	v_and_b32_e32 v18, 0xffff0000, v33
	v_fmac_f32_e32 v42, v90, v90
	v_and_b32_e32 v20, 0xffff0000, v37
	v_pk_mul_f32 v[18:19], v[34:35], v[18:19]
	v_fmac_f32_e32 v42, v88, v88
	v_fma_f32 v19, v41, v20, v19
	v_fmac_f32_e32 v42, v89, v89
	v_add_f32_e32 v150, v18, v19
	v_fmac_f32_e32 v42, v94, v94
	v_fmac_f32_e32 v42, v150, v150
	v_and_b32_e32 v38, 0xffff0000, v5
	v_lshlrev_b32_e32 v39, 16, v5
	ds_bpermute_b32 v5, v140, v42
	v_lshlrev_b32_e32 v82, 16, v14
	v_and_b32_e32 v80, 0xffff0000, v14
	v_lshlrev_b32_e32 v78, 16, v15
	v_and_b32_e32 v76, 0xffff0000, v15
	s_waitcnt lgkmcnt(0)
	v_add_f32_e32 v5, v42, v5
	ds_bpermute_b32 v18, v141, v5
	v_lshlrev_b32_e32 v48, 16, v16
	v_and_b32_e32 v46, 0xffff0000, v16
	v_lshlrev_b32_e32 v44, 16, v17
	v_and_b32_e32 v42, 0xffff0000, v17
	s_waitcnt lgkmcnt(0)
	v_add_f32_e32 v5, v5, v18
	ds_bpermute_b32 v18, v142, v5
	s_waitcnt vmcnt(1)
	v_and_b32_e32 v118, 0xffff0000, v7
	v_mul_f32_e32 v3, 0xbfb8aa3b, v118
	v_exp_f32_e32 v3, v3
	v_and_b32_e32 v136, 0xffff0000, v6
	s_waitcnt lgkmcnt(0)
	v_add_f32_e32 v5, v5, v18
	ds_bpermute_b32 v18, v143, v5
	v_and_b32_e32 v137, 0xffff0000, v2
	v_mul_f32_e32 v2, 0xbfb8aa3b, v136
	v_exp_f32_e32 v2, v2
	v_lshlrev_b32_e32 v102, 16, v24
	s_waitcnt lgkmcnt(0)
	v_add_f32_e32 v5, v5, v18
	ds_bpermute_b32 v18, v144, v5
	v_lshlrev_b32_e32 v110, 16, v7
	v_add_f32_e32 v3, 1.0, v3
	v_rcp_f32_e32 v124, v3
	v_mul_f32_e32 v3, 0xbfb8aa3b, v110
	s_waitcnt lgkmcnt(0)
	v_add_f32_e32 v5, v5, v18
	ds_bpermute_b32 v18, v145, v5
	v_exp_f32_e32 v3, v3
	v_add_f32_e32 v2, 1.0, v2
	v_rcp_f32_e32 v138, v2
	v_mul_f32_e32 v2, v131, v131
	s_waitcnt lgkmcnt(0)
	v_add_f32_e32 v5, v5, v18
	v_fmamk_f32 v5, v5, 0x3a800000, v215
	v_cmp_gt_f32_e32 vcc, s33, v5
	v_mul_f32_e32 v18, 0x4f800000, v5
	v_fmac_f32_e32 v2, v133, v133
	v_cndmask_b32_e32 v5, v5, v18, vcc
	v_sqrt_f32_e32 v18, v5
	v_fmac_f32_e32 v2, v109, v109
	v_lshlrev_b32_e32 v108, 16, v23
	v_and_b32_e32 v122, 0xffff0000, v23
	v_add_u32_e32 v19, -1, v18
	v_fma_f32 v20, -v19, v18, v5
	v_cmp_ge_f32_e64 s[0:1], 0, v20
	v_add_u32_e32 v20, 1, v18
	v_lshlrev_b32_e32 v130, 16, v22
	v_cndmask_b32_e64 v19, v18, v19, s[0:1]
	v_fma_f32 v18, -v20, v18, v5
	v_cmp_lt_f32_e64 s[0:1], 0, v18
	v_and_b32_e32 v132, 0xffff0000, v22
	v_add_f32_e32 v3, 1.0, v3
	v_cndmask_b32_e64 v18, v19, v20, s[0:1]
	v_mul_f32_e32 v19, 0x37800000, v18
	v_cndmask_b32_e32 v18, v18, v19, vcc
	v_cmp_class_f32_e32 vcc, v5, v216
	v_fmac_f32_e32 v2, v123, v123
	v_rcp_f32_e32 v120, v3
	v_cndmask_b32_e32 v5, v18, v5, vcc
	v_div_scale_f32 v18, s[0:1], v5, v5, 1.0
	v_rcp_f32_e32 v19, v18
	v_fmac_f32_e32 v2, v103, v103
	v_pk_mul_f32 v[40:41], v[38:39], v[38:39]
	v_lshlrev_b32_e32 v128, 16, v6
	v_fma_f32 v20, -v18, v19, 1.0
	v_fmac_f32_e32 v19, v20, v19
	v_div_scale_f32 v20, vcc, 1.0, v5, 1.0
	v_mul_f32_e32 v21, v20, v19
	v_fma_f32 v30, -v18, v21, v20
	v_fmac_f32_e32 v21, v30, v19
	v_fma_f32 v18, -v18, v21, v20
	v_div_fmas_f32 v18, v18, v19, v21
	v_div_fixup_f32 v151, v18, v5, 1.0
	global_load_dwordx4 v[14:17], v[58:59], off offset:16
	global_load_dwordx4 v[18:21], v[58:59], off
	global_load_dwordx4 v[30:33], v[60:61], off offset:16
	global_load_dwordx4 v[34:37], v[60:61], off
	v_mul_f32_e32 v81, v79, v151
	v_mul_f32_e32 v83, v77, v151
	v_mul_f32_e32 v77, v85, v151
	v_mul_f32_e32 v47, v47, v151
	v_mul_f32_e32 v49, v84, v151
	v_lshlrev_b32_e32 v84, 16, v25
	v_mul_f32_e32 v79, v86, v151
	v_lshlrev_b32_e32 v85, 16, v13
	v_mul_f32_e32 v13, 0xbfb8aa3b, v102
	v_exp_f32_e32 v13, v13
	v_mul_f32_e32 v5, 0xbfb8aa3b, v82
	v_exp_f32_e32 v5, v5
	v_mul_f32_e32 v43, v43, v151
	v_add_f32_e32 v13, 1.0, v13
	v_rcp_f32_e32 v104, v13
	v_and_b32_e32 v13, 0xffff0000, v12
	v_add_f32_e32 v5, 1.0, v5
	v_fmac_f32_e32 v2, v13, v13
	v_rcp_f32_e32 v96, v5
	v_fmac_f32_e32 v2, v85, v85
	v_fmac_f32_e32 v2, v93, v93
	v_fmac_f32_e32 v2, v129, v129
	v_fmac_f32_e32 v2, v137, v137
	v_fmac_f32_e32 v2, v111, v111
	v_fmac_f32_e32 v2, v119, v119
	v_mul_f32_e32 v95, v90, v151
	v_and_b32_e32 v12, 0xffff0000, v24
	v_mul_f32_e32 v24, 0xbfb8aa3b, v12
	v_mul_f32_e32 v11, 0xbfb8aa3b, v122
	v_exp_f32_e32 v24, v24
	v_exp_f32_e32 v11, v11
	v_mul_f32_e32 v10, 0xbfb8aa3b, v132
	v_exp_f32_e32 v10, v10
	v_add_f32_e32 v24, 1.0, v24
	v_add_f32_e32 v11, 1.0, v11
	v_rcp_f32_e32 v106, v24
	v_mul_f32_e32 v24, 0xbfb8aa3b, v108
	v_rcp_f32_e32 v126, v11
	v_mul_f32_e32 v11, 0xbfb8aa3b, v130
	v_exp_f32_e32 v24, v24
	v_exp_f32_e32 v11, v11
	v_mul_f32_e32 v45, v92, v151
	v_add_f32_e32 v10, 1.0, v10
	v_add_f32_e32 v24, 1.0, v24
	v_add_f32_e32 v11, 1.0, v11
	v_rcp_f32_e32 v112, v24
	v_rcp_f32_e32 v24, v11
	v_rcp_f32_e32 v134, v10
	v_and_b32_e32 v92, 0xffff0000, v25
	v_mul_f32_e32 v10, 0xbfb8aa3b, v92
	v_exp_f32_e32 v10, v10
	v_mul_f32_e32 v115, v87, v151
	v_mul_f32_e32 v117, v99, v151
	v_mul_f32_e32 v91, v91, v151
	v_add_f32_e32 v10, 1.0, v10
	v_rcp_f32_e32 v10, v10
	s_waitcnt vmcnt(0)
; __device__ __forceinline__ unsigned pk2(float lo, float hi) { unsigned r; asm("v_cvt_pk_bf16_f32 %0, %1, %2" : "=v"(r) : "v"(lo), "v"(hi)); return r; }
; __device__ __forceinline__ float bflo(unsigned w) { return __uint_as_float(w << 16); }
; __device__ __forceinline__ float bfhi(unsigned w) { return __uint_as_float(w & 0xffff0000u); }
; __device__ __forceinline__ void gate_row(int m, int lane, const bf16_t* __restrict__ YA, const bf16_t* __restrict__ YB, const float* __restrict__ LSE, const bf16_t* __restrict__ PROJ, ...
;     ...
;     const float ra = 1.0f / sqrtf(wave_sum(ssa) * (1.0f / DA) + EPS), rb = 1.0f / sqrtf(wave_sum(ssb) * (1.0f / DB) + EPS);
; #pragma unroll
;     for (int j = 0; j < 2; ++j) { const int c = lane + 64 * j;
;         const float gaf[8] = {bflo(ga[j].x), bfhi(ga[j].x), bflo(ga[j].y), bfhi(ga[j].y), bflo(ga[j].z), bfhi(ga[j].z), bflo(ga[j].w), bfhi(ga[j].w)};
;         const float gbf[8] = {bflo(gb[j].x), bfhi(gb[j].x), bflo(gb[j].y), bfhi(gb[j].y), bflo(gb[j].z), bfhi(gb[j].z), bflo(gb[j].w), bfhi(gb[j].w)};
;         const f32x4 wa0 = *(const f32x4*)(wa + 8 * c), wa1 = *(const f32x4*)(wa + 8 * c + 4), wb0 = *(const f32x4*)(wb + 8 * c), wb1 = *(const f32x4*)(wb + 8 * c + 4);
;         float za[8], zb[8];
; #pragma unroll
;         for (int i = 0; i < 8; ++i) { const float wai = i < 4 ? wa0[i & 3] : wa1[i & 3], wbi = i < 4 ? wb0[i & 3] : wb1[i & 3];
;             const float sa = gaf[i] * __builtin_amdgcn_rcpf(1.0f + __builtin_amdgcn_exp2f(-1.4426950408889634f * gaf[i])), sb = gbf[i] * __builtin_amdgcn_rcpf(1.0f + __builtin_amdgcn_exp2f(-1.4426950408889634f * gbf[i]));
;             za[i] = ya[j][i] * ra * wai * sa; zb[i] = yb[j][i] * rb * wbi * sb; }
;         v4u oa, ob; oa.x = pk2(za[0], za[1]); oa.y = pk2(za[2], za[3]); oa.z = pk2(za[4], za[5]); oa.w = pk2(za[6], za[7]);
;         ob.x = pk2(zb[0], zb[1]); ob.y = pk2(zb[2], zb[3]); ob.z = pk2(zb[4], zb[5]); ob.w = pk2(zb[6], zb[7]);
;         *(v4u*)(H + (size_t)m * DM + 8 * c) = oa; *(v4u*)(H + (size_t)m * DM + DA + 8 * c) = ob; }
	v_mov_b32_e32 v97, v34
	v_mul_f32_e32 v34, 0xbfb8aa3b, v80
	v_exp_f32_e32 v34, v34
	v_pk_mul_f32 v[82:83], v[96:97], v[82:83]
	v_and_b32_e32 v97, 0xffff0000, v4
	v_mul_f32_e32 v5, v82, v83
	v_add_f32_e32 v34, 1.0, v34
	v_rcp_f32_e32 v34, v34
	v_mul_f32_e32 v83, v89, v151
	v_lshlrev_b32_e32 v89, 16, v4
	v_fmac_f32_e32 v2, v89, v89
	v_pk_mul_f32 v[34:35], v[34:35], v[80:81]
	v_mov_b32_e32 v81, v36
	v_mul_f32_e32 v35, v34, v35
	v_mul_f32_e32 v34, 0xbfb8aa3b, v78
	v_exp_f32_e32 v34, v34
	v_fmac_f32_e32 v2, v97, v97
	v_add_f32_e32 v2, v41, v2
	v_add_f32_e32 v2, v40, v2
	v_add_f32_e32 v34, 1.0, v34
	v_rcp_f32_e32 v80, v34
	v_mul_f32_e32 v34, 0xbfb8aa3b, v76
	v_exp_f32_e32 v34, v34
	v_and_b32_e32 v96, 0xffff0000, v8
	v_mul_f32_e32 v4, 0xbfb8aa3b, v96
	v_exp_f32_e32 v4, v4
	v_add_f32_e32 v34, 1.0, v34
	v_rcp_f32_e32 v36, v34
	v_pk_mul_f32 v[78:79], v[80:81], v[78:79]
	v_mul_f32_e32 v81, v88, v151
	v_lshlrev_b32_e32 v88, 16, v8
	v_pk_mul_f32 v[36:37], v[36:37], v[76:77]
	v_mov_b32_e32 v77, v30
	v_mul_f32_e32 v30, 0xbfb8aa3b, v46
	v_exp_f32_e32 v30, v30
	v_add_f32_e32 v4, 1.0, v4
	v_rcp_f32_e32 v100, v4
	v_mul_f32_e32 v4, 0xbfb8aa3b, v88
	v_add_f32_e32 v30, 1.0, v30
	v_rcp_f32_e32 v30, v30
	v_exp_f32_e32 v4, v4
	v_mul_f32_e32 v34, 0xbfb8aa3b, v48
	v_exp_f32_e32 v34, v34
	v_pk_mul_f32 v[30:31], v[30:31], v[46:47]
	v_mov_b32_e32 v47, v32
	v_mul_f32_e32 v31, v30, v31
	v_mul_f32_e32 v30, 0xbfb8aa3b, v44
	v_exp_f32_e32 v30, v30
	v_mul_f32_e32 v37, v36, v37
	v_and_b32_e32 v36, 0xffff0000, v27
	v_add_f32_e32 v4, 1.0, v4
	v_add_f32_e32 v30, 1.0, v30
	v_rcp_f32_e32 v46, v30
	v_mul_f32_e32 v30, 0xbfb8aa3b, v84
	v_exp_f32_e32 v30, v30
	v_rcp_f32_e32 v98, v4
	v_mul_f32_e32 v4, 0xbfb8aa3b, v36
	v_add_f32_e32 v34, 1.0, v34
	v_add_f32_e32 v30, 1.0, v30
	v_rcp_f32_e32 v86, v30
	v_mul_f32_e32 v30, 0xbfb8aa3b, v42
	v_exp_f32_e32 v30, v30
	v_exp_f32_e32 v4, v4
	v_rcp_f32_e32 v76, v34
	v_lshlrev_b32_e32 v34, 16, v27
	v_add_f32_e32 v30, 1.0, v30
	v_rcp_f32_e32 v32, v30
	v_lshlrev_b32_e32 v30, 16, v26
	v_add_f32_e32 v4, 1.0, v4
	v_pk_mul_f32 v[48:49], v[76:77], v[48:49]
	v_pk_mul_f32 v[22:23], v[32:33], v[42:43]
	v_and_b32_e32 v32, 0xffff0000, v26
	v_mul_f32_e32 v3, 0xbfb8aa3b, v32
	v_exp_f32_e32 v3, v3
	v_mul_f32_e32 v77, v94, v151
	v_rcp_f32_e32 v94, v4
	v_mul_f32_e32 v4, 0xbfb8aa3b, v34
	v_add_f32_e32 v3, 1.0, v3
	v_rcp_f32_e32 v116, v3
	v_mul_f32_e32 v3, 0xbfb8aa3b, v30
	v_exp_f32_e32 v3, v3
	v_exp_f32_e32 v4, v4
	v_mul_f32_e32 v79, v78, v79
	v_pk_mul_f32 v[44:45], v[46:47], v[44:45]
	v_add_f32_e32 v3, 1.0, v3
	v_rcp_f32_e32 v114, v3
	ds_bpermute_b32 v3, v140, v2
	v_add_f32_e32 v4, 1.0, v4
	v_rcp_f32_e32 v90, v4
	v_and_b32_e32 v78, 0xffff0000, v28
	v_mul_f32_e32 v45, v44, v45
	s_waitcnt lgkmcnt(0)
	v_add_f32_e32 v2, v2, v3
	ds_bpermute_b32 v3, v141, v2
	v_lshlrev_b32_e32 v44, 16, v9
	v_lshlrev_b32_e32 v42, 16, v28
	v_and_b32_e32 v28, 0xffff0000, v9
	v_mul_f32_e32 v9, 0xbfb8aa3b, v78
	s_waitcnt lgkmcnt(0)
	v_add_f32_e32 v2, v2, v3
	ds_bpermute_b32 v3, v142, v2
	v_exp_f32_e32 v9, v9
	v_lshlrev_b32_e32 v46, 16, v29
	v_mul_f32_e32 v11, 0xbfb8aa3b, v46
	v_exp_f32_e32 v11, v11
	s_waitcnt lgkmcnt(0)
	v_add_f32_e32 v2, v2, v3
	ds_bpermute_b32 v3, v143, v2
	v_add_f32_e32 v9, 1.0, v9
	v_rcp_f32_e32 v82, v9
	v_mul_f32_e32 v9, 0xbfb8aa3b, v42
	v_exp_f32_e32 v9, v9
	s_waitcnt lgkmcnt(0)
	v_add_f32_e32 v2, v2, v3
	ds_bpermute_b32 v3, v144, v2
	v_add_f32_e32 v11, 1.0, v11
	v_rcp_f32_e32 v76, v11
	v_mul_f32_e32 v11, 0xbfb8aa3b, v44
	v_exp_f32_e32 v11, v11
	s_waitcnt lgkmcnt(0)
	v_add_f32_e32 v2, v2, v3
	ds_bpermute_b32 v3, v145, v2
	v_add_f32_e32 v9, 1.0, v9
	v_rcp_f32_e32 v80, v9
	v_add_f32_e32 v11, 1.0, v11
	v_mul_f32_e32 v49, v48, v49
	s_waitcnt lgkmcnt(0)
	v_add_f32_e32 v2, v2, v3
	v_fmamk_f32 v2, v2, 0x3a800000, v215
	v_cmp_gt_f32_e32 vcc, s33, v2
	v_mul_f32_e32 v3, 0x4f800000, v2
	v_rcp_f32_e32 v48, v11
	v_cndmask_b32_e32 v2, v2, v3, vcc
	v_sqrt_f32_e32 v3, v2
	v_mul_f32_e32 v33, v22, v23
	v_lshl_add_u64 v[22:23], v[66:67], 0, s[28:29]
	v_and_b32_e32 v26, 0xffff0000, v29
	v_add_u32_e32 v4, -1, v3
	v_fma_f32 v6, -v4, v3, v2
	v_cmp_ge_f32_e64 s[0:1], 0, v6
	v_add_u32_e32 v6, 1, v3
	s_nop 0
	v_cndmask_b32_e64 v4, v3, v4, s[0:1]
	v_fma_f32 v3, -v6, v3, v2
	v_cmp_lt_f32_e64 s[0:1], 0, v3
	s_nop 1
	v_cndmask_b32_e64 v3, v4, v6, s[0:1]
	v_mul_f32_e32 v4, 0x37800000, v3
	v_cndmask_b32_e32 v3, v3, v4, vcc
	v_cmp_class_f32_e32 vcc, v2, v216
	s_nop 1
	v_cndmask_b32_e32 v2, v3, v2, vcc
	v_div_scale_f32 v3, s[0:1], v2, v2, 1.0
	v_rcp_f32_e32 v4, v3
	s_nop 0
	v_fma_f32 v6, -v3, v4, 1.0
	v_fmac_f32_e32 v4, v6, v4
	v_div_scale_f32 v6, vcc, 1.0, v2, 1.0
	v_mul_f32_e32 v7, v6, v4
	v_fma_f32 v8, -v3, v7, v6
	v_fmac_f32_e32 v7, v8, v4
	v_fma_f32 v3, -v3, v7, v6
	v_div_fmas_f32 v3, v3, v4, v7
	v_div_fixup_f32 v25, v3, v2, 1.0
	v_pk_mul_f32 v[2:3], v[24:25], v[130:131]
	v_mov_b32_e32 v135, v25
	v_mul_f32_e32 v3, v3, v18
	v_mul_f32_e32 v4, v2, v3
	v_pk_mul_f32 v[2:3], v[134:135], v[132:133]
	v_mov_b32_e32 v113, v25
	v_mul_f32_e32 v3, v3, v19
	v_mul_f32_e32 v6, v2, v3
	v_pk_mul_f32 v[2:3], v[112:113], v[108:109]
	v_mov_b32_e32 v127, v25
	v_mul_f32_e32 v3, v3, v20
	v_mul_f32_e32 v7, v2, v3
	v_pk_mul_f32 v[2:3], v[126:127], v[122:123]
	v_mov_b32_e32 v105, v25
	v_mul_f32_e32 v3, v3, v21
	v_mul_f32_e32 v8, v2, v3
	v_pk_mul_f32 v[2:3], v[104:105], v[102:103]
	v_mov_b32_e32 v107, v25
	v_mul_f32_e32 v3, v3, v14
	v_mul_f32_e32 v9, v2, v3
	v_pk_mul_f32 v[2:3], v[106:107], v[12:13]
	v_mov_b32_e32 v87, v25
	v_mul_f32_e32 v3, v3, v15
	v_mul_f32_e32 v12, v2, v3
	v_pk_mul_f32 v[2:3], v[86:87], v[84:85]
	v_mov_b32_e32 v11, v25
	v_mul_f32_e32 v3, v3, v16
	v_mul_f32_e32 v13, v2, v3
	v_pk_mul_f32 v[2:3], v[10:11], v[92:93]
	v_cvt_pk_bf16_f32 v6, v4, v6
	v_cvt_pk_bf16_f32 v7, v7, v8
	v_cvt_pk_bf16_f32 v8, v9, v12
	v_cvt_pk_bf16_f32 v4, v49, v31
	v_mul_f32_e32 v49, v25, v39
	v_mul_f32_e32 v3, v3, v17
	v_mul_f32_e32 v2, v2, v3
	v_cvt_pk_bf16_f32 v9, v13, v2
	v_cvt_pk_bf16_f32 v2, v5, v35
	v_cvt_pk_bf16_f32 v3, v79, v37
	v_cvt_pk_bf16_f32 v5, v45, v33
	global_store_dwordx4 v[22:23], v[6:9], off offset:-2048
	global_store_dwordx4 v[22:23], v[2:5], off
	global_load_dwordx4 v[2:5], v[58:59], off offset:2064
	s_nop 0
	global_load_dwordx4 v[10:13], v[58:59], off offset:2048
	global_load_dwordx4 v[6:9], v[60:61], off offset:2064
	global_load_dwordx4 v[14:17], v[60:61], off offset:2048
	v_mov_b32_e32 v101, v25
	v_mov_b32_e32 v99, v25
	v_mov_b32_e32 v125, v25
	v_mov_b32_e32 v121, v25
	v_mov_b32_e32 v139, v25
	s_waitcnt vmcnt(3)
; __device__ __forceinline__ void gate_row(int m, int lane, const bf16_t* __restrict__ YA, const bf16_t* __restrict__ YB, const float* __restrict__ LSE, const bf16_t* __restrict__ PROJ, ...
;     ...
; #pragma unroll
;     for (int j = 0; j < 2; ++j) { const int c = lane + 64 * j, hh = c >> 4;
;         a[j] = *(const v4u*)(YA + (size_t)m * DA + 8 * c);
;         b0[j] = *(const v4u*)(YB + ((size_t)0 * M + m) * DB + 8 * c); b1[j] = *(const v4u*)(YB + ((size_t)1 * M + m) * DB + 8 * c); b2[j] = *(const v4u*)(YB + ((size_t)2 * M + m) * DB + 8 * c);
;         l0[j] = LSE[((size_t)0 * M + m) * 8 + hh]; l1[j] = LSE[((size_t)1 * M + m) * 8 + hh]; l2[j] = LSE[((size_t)2 * M + m) * 8 + hh];
;         ga[j] = *(const v4u*)(PROJ + ((size_t)(H_GA + (c >> 4)) * M + m) * HD + 8 * (c & 15)); gb[j] = *(const v4u*)(PROJ + ((size_t)(H_GB + (c >> 4)) * M + m) * HD + 8 * (c & 15)); }
;     ...
;     for (int j = 0; j < 2; ++j) { const int c = lane + 64 * j;
;         const float gaf[8] = {bflo(ga[j].x), bfhi(ga[j].x), bflo(ga[j].y), bfhi(ga[j].y), bflo(ga[j].z), bfhi(ga[j].z), bflo(ga[j].w), bfhi(ga[j].w)};
;         const float gbf[8] = {bflo(gb[j].x), bfhi(gb[j].x), bflo(gb[j].y), bfhi(gb[j].y), bflo(gb[j].z), bfhi(gb[j].z), bflo(gb[j].w), bfhi(gb[j].w)};
;         const f32x4 wa0 = *(const f32x4*)(wa + 8 * c), wa1 = *(const f32x4*)(wa + 8 * c + 4), wb0 = *(const f32x4*)(wb + 8 * c), wb1 = *(const f32x4*)(wb + 8 * c + 4);
;         float za[8], zb[8];
; #pragma unroll
;         for (int i = 0; i < 8; ++i) { const float wai = i < 4 ? wa0[i & 3] : wa1[i & 3], wbi = i < 4 ? wb0[i & 3] : wb1[i & 3];
;             const float sa = gaf[i] * __builtin_amdgcn_rcpf(1.0f + __builtin_amdgcn_exp2f(-1.4426950408889634f * gaf[i])), sb = gbf[i] * __builtin_amdgcn_rcpf(1.0f + __builtin_amdgcn_exp2f(-1.4426950408889634f * gbf[i]));
;             za[i] = ya[j][i] * ra * wai * sa; zb[i] = yb[j][i] * rb * wbi * sb; }
;         v4u oa, ob; oa.x = pk2(za[0], za[1]); oa.y = pk2(za[2], za[3]); oa.z = pk2(za[4], za[5]); oa.w = pk2(za[6], za[7]);
;         ob.x = pk2(zb[0], zb[1]); ob.y = pk2(zb[2], zb[3]); ob.z = pk2(zb[4], zb[5]); ob.w = pk2(zb[6], zb[7]);
;         *(v4u*)(H + (size_t)m * DM + 8 * c) = oa; *(v4u*)(H + (size_t)m * DM + DA + 8 * c) = ob; }
; __global__ void __launch_bounds__(512, 2) mk_fwd(Params p) {
;     ...
;                     if (m + NGW < M) gate_row(m + NGW, lane, YA, YB, LSE, PROJ, wa, wb, H);
	v_mov_b32_e32 v45, v4
	v_mov_b32_e32 v29, v5
	s_waitcnt vmcnt(1)
	v_mov_b32_e32 v47, v8
	v_pk_mul_f32 v[18:19], v[76:77], v[46:47]
	v_mov_b32_e32 v79, v7
	v_mul_f32_e32 v20, v18, v19
	v_pk_mul_f32 v[18:19], v[48:49], v[44:45]
	v_mov_b32_e32 v43, v6
	v_mul_f32_e32 v8, v18, v19
	v_pk_mul_f32 v[18:19], v[82:83], v[78:79]
	v_pk_mul_f32 v[6:7], v[80:81], v[42:43]
	v_mul_f32_e32 v21, v18, v19
	v_pk_mul_f32 v[18:19], v[100:101], v[96:97]
	s_waitcnt vmcnt(0)
	v_mov_b32_e32 v37, v17
	v_mul_f32_e32 v3, v19, v3
	v_mul_f32_e32 v19, v6, v7
	v_pk_mul_f32 v[6:7], v[98:99], v[88:89]
	v_mul_f32_e32 v18, v18, v3
	v_mul_f32_e32 v2, v7, v2
	v_mul_f32_e32 v6, v6, v2
	v_pk_mul_f32 v[2:3], v[94:95], v[36:37]
	v_mov_b32_e32 v35, v16
	v_mul_f32_e32 v7, v2, v3
	v_pk_mul_f32 v[2:3], v[124:125], v[118:119]
	v_mov_b32_e32 v33, v15
	v_mul_f32_e32 v3, v3, v13
	v_mul_f32_e32 v13, v2, v3
	v_pk_mul_f32 v[2:3], v[90:91], v[34:35]
	v_mov_b32_e32 v31, v14
	v_mul_f32_e32 v16, v2, v3
	v_pk_mul_f32 v[2:3], v[120:121], v[110:111]
	v_mul_f32_e32 v5, v150, v151
	v_mul_f32_e32 v3, v3, v12
	v_mul_f32_e32 v12, v2, v3
	v_pk_mul_f32 v[2:3], v[116:117], v[32:33]
	v_mov_b32_e32 v27, v9
	v_mul_f32_e32 v15, v2, v3
	v_pk_mul_f32 v[2:3], v[138:139], v[136:137]
	v_cvt_pk_bf16_f32 v7, v16, v7
	s_nop 0
	v_mul_f32_e32 v3, v3, v11
	v_mul_f32_e32 v11, v2, v3
	v_pk_mul_f32 v[2:3], v[114:115], v[30:31]
	s_nop 0
	v_mul_f32_e32 v14, v2, v3
	v_mul_f32_e32 v2, 0xbfb8aa3b, v128
	v_exp_f32_e32 v2, v2
	s_nop 0
	v_add_f32_e32 v2, 1.0, v2
	v_rcp_f32_e32 v24, v2
	s_nop 0
	v_pk_mul_f32 v[2:3], v[24:25], v[128:129]
	s_nop 0
	v_mul_f32_e32 v3, v3, v10
	v_mul_f32_e32 v10, v2, v3
	v_mul_f32_e32 v2, 0xbfb8aa3b, v28
	v_exp_f32_e32 v2, v2
	v_mul_f32_e32 v3, 0xbfb8aa3b, v26
	v_exp_f32_e32 v3, v3
	v_add_f32_e32 v2, 1.0, v2
	v_rcp_f32_e32 v2, v2
	v_add_f32_e32 v3, 1.0, v3
	v_rcp_f32_e32 v4, v3
	v_mul_f32_e32 v3, v25, v38
	v_pk_mul_f32 v[2:3], v[2:3], v[28:29]
	s_nop 0
	v_mul_f32_e32 v17, v2, v3
	v_pk_mul_f32 v[2:3], v[4:5], v[26:27]
	v_cvt_pk_bf16_f32 v4, v6, v18
	v_cvt_pk_bf16_f32 v5, v8, v17
	v_cvt_pk_bf16_f32 v6, v14, v15
	v_cvt_pk_bf16_f32 v8, v19, v21
	s_nop 0
	v_mul_f32_e32 v9, v2, v3
	v_cvt_pk_bf16_f32 v2, v10, v11
	v_cvt_pk_bf16_f32 v3, v12, v13
	v_cvt_pk_bf16_f32 v9, v20, v9
	global_store_dwordx4 v[22:23], v[2:5], off offset:-1024
	global_store_dwordx4 v[22:23], v[6:9], off offset:1024
	s_cbranch_scc1 .LBB0_40
	s_ashr_i32 s45, s44, 31
	s_lshl_b64 s[10:11], s[44:45], 11
	s_add_u32 s0, s52, s10
	s_addc_u32 s1, s8, s11
	s_add_u32 s50, s4, s10
	s_addc_u32 s51, s5, s11
	s_add_u32 s10, s44, 0x4000
	s_addc_u32 s11, s45, 0
	s_lshl_b64 s[12:13], s[10:11], 11
	s_add_u32 s12, s4, s12
	s_addc_u32 s13, s5, s13
	s_add_u32 s14, s44, 0x8000
	s_addc_u32 s15, s45, 0
	global_load_dwordx4 v[14:17], v146, s[50:51] nt
	global_load_dwordx4 v[18:21], v146, s[12:13] nt
	global_load_dwordx4 v[2:5], v148, s[12:13] nt
	s_lshl_b64 s[12:13], s[14:15], 11
	s_add_u32 s78, s4, s12
	s_addc_u32 s79, s5, s13
	s_lshl_b64 s[12:13], s[44:45], 5
	s_add_u32 s12, s6, s12
	s_addc_u32 s13, s7, s13
	s_lshl_b64 s[10:11], s[10:11], 5
	s_add_u32 s10, s6, s10
	s_addc_u32 s11, s7, s11
	s_lshl_b64 s[14:15], s[14:15], 5
	s_add_u32 s14, s6, s14
	global_load_dwordx4 v[10:13], v146, s[78:79] nt
	s_addc_u32 s15, s7, s15
	global_load_dword v80, v147, s[12:13] nt
	global_load_dword v81, v147, s[10:11] nt
	global_load_dword v82, v147, s[14:15] nt
	global_load_dword v83, v149, s[12:13] nt
	global_load_dword v84, v149, s[10:11] nt
	global_load_dword v85, v149, s[14:15] nt
	v_lshl_add_u64 v[6:7], s[44:45], 0, v[52:53]
	v_lshl_add_u64 v[8:9], s[44:45], 0, v[0:1]
	v_lshlrev_b64 v[6:7], 8, v[6:7]
	v_lshlrev_b64 v[8:9], 8, v[8:9]
	v_lshl_add_u64 v[6:7], v[50:51], 0, v[6:7]
	v_lshl_add_u64 v[8:9], v[50:51], 0, v[8:9]
	global_load_dwordx4 v[26:29], v[6:7], off nt
	global_load_dwordx4 v[22:25], v148, s[0:1] nt
	global_load_dwordx4 v[30:33], v146, s[0:1] nt
	global_load_dwordx4 v[34:37], v148, s[50:51] nt
	global_load_dwordx4 v[38:41], v148, s[78:79] nt
	s_nop 0
	global_load_dwordx4 v[6:9], v[8:9], off nt
	s_waitcnt vmcnt(15)
	v_lshlrev_b32_e32 v43, 16, v14
	s_waitcnt vmcnt(13)
	v_lshlrev_b32_e32 v93, 16, v2
	v_and_b32_e32 v94, 0xffff0000, v2
	v_and_b32_e32 v45, 0xffff0000, v14
	v_lshlrev_b32_e32 v95, 16, v3
	v_and_b32_e32 v96, 0xffff0000, v3
	v_lshlrev_b32_e32 v49, 16, v16
	v_and_b32_e32 v77, 0xffff0000, v16
	v_lshlrev_b32_e32 v86, 16, v18
	v_and_b32_e32 v87, 0xffff0000, v18
	v_lshlrev_b32_e32 v89, 16, v20
	v_and_b32_e32 v90, 0xffff0000, v20
	s_waitcnt vmcnt(9)
	v_max3_f32 v2, v80, v81, v82
	v_lshlrev_b32_e32 v42, 16, v10
	v_and_b32_e32 v44, 0xffff0000, v10
	v_lshlrev_b32_e32 v46, 16, v11
	v_and_b32_e32 v14, 0xffff0000, v11
	s_waitcnt vmcnt(6)
	v_max3_f32 v3, v83, v84, v85
	v_sub_f32_e32 v10, v80, v2
	v_sub_f32_e32 v11, v81, v2
	v_lshlrev_b32_e32 v48, 16, v12
	v_and_b32_e32 v76, 0xffff0000, v12
	v_sub_f32_e32 v2, v82, v2
	v_sub_f32_e32 v12, v83, v3
	v_sub_f32_e32 v16, v84, v3
	v_sub_f32_e32 v18, v85, v3
	v_exp_f32_e32 v3, v10
	v_exp_f32_e32 v20, v11
	v_lshlrev_b32_e32 v91, 16, v21
	v_and_b32_e32 v92, 0xffff0000, v21
	v_exp_f32_e32 v11, v12
	v_exp_f32_e32 v21, v16
	v_exp_f32_e32 v2, v2
	v_exp_f32_e32 v10, v18
	v_add_f32_e32 v12, v3, v20
	v_add_f32_e32 v16, v11, v21
	v_add_f32_e32 v12, v2, v12
	v_rcp_f32_e32 v12, v12
	v_add_f32_e32 v16, v10, v16
	v_rcp_f32_e32 v18, v16
	v_lshlrev_b32_e32 v47, 16, v15
	v_and_b32_e32 v15, 0xffff0000, v15
	v_lshlrev_b32_e32 v79, 16, v17
	v_and_b32_e32 v17, 0xffff0000, v17
	v_lshlrev_b32_e32 v78, 16, v13
	v_and_b32_e32 v16, 0xffff0000, v13
	v_pk_mul_f32 v[2:3], v[2:3], v[12:13] op_sel_hi:[1,0]
	v_lshlrev_b32_e32 v88, 16, v19
	v_and_b32_e32 v19, 0xffff0000, v19
	v_mul_f32_e32 v80, v20, v12
	v_mul_f32_e32 v81, v21, v18
	v_pk_mul_f32 v[12:13], v[2:3], v[42:43]
	v_pk_mul_f32 v[20:21], v[2:3], v[44:45]
	v_pk_mul_f32 v[42:43], v[2:3], v[46:47]
	v_pk_mul_f32 v[14:15], v[2:3], v[14:15]
	v_pk_mul_f32 v[44:45], v[2:3], v[48:49]
	v_pk_mul_f32 v[46:47], v[2:3], v[76:77]
	v_pk_mul_f32 v[48:49], v[2:3], v[78:79]
	v_pk_mul_f32 v[2:3], v[2:3], v[16:17]
	v_fma_f32 v15, v80, v19, v15
	v_fma_f32 v19, v80, v89, v45
	v_fma_f32 v3, v80, v92, v3
	v_add_f32_e32 v99, v2, v3
	v_pk_mul_f32 v[2:3], v[10:11], v[18:19] op_sel_hi:[1,0]
	s_waitcnt vmcnt(2)
; __device__ __forceinline__ void gate_row(int m, int lane, const bf16_t* __restrict__ YA, const bf16_t* __restrict__ YB, const float* __restrict__ LSE, const bf16_t* __restrict__ PROJ, ...
;     ...
;         const float mx = fmaxf(l0[j], fmaxf(l1[j], l2[j])); const float e0 = __builtin_amdgcn_exp2f(l0[j] - mx), e1 = __builtin_amdgcn_exp2f(l1[j] - mx), e2 = __builtin_amdgcn_exp2f(l2[j] - mx);
;         const float inv = __builtin_amdgcn_rcpf(e0 + e1 + e2); const float w0 = e0 * inv, w1 = e1 * inv, w2 = e2 * inv;
;         yb[j][0] = w0 * bflo(b0[j].x) + w1 * bflo(b1[j].x) + w2 * bflo(b2[j].x); yb[j][1] = w0 * bfhi(b0[j].x) + w1 * bfhi(b1[j].x) + w2 * bfhi(b2[j].x);
;         yb[j][2] = w0 * bflo(b0[j].y) + w1 * bflo(b1[j].y) + w2 * bflo(b2[j].y); yb[j][3] = w0 * bfhi(b0[j].y) + w1 * bfhi(b1[j].y) + w2 * bfhi(b2[j].y);
;         yb[j][4] = w0 * bflo(b0[j].z) + w1 * bflo(b1[j].z) + w2 * bflo(b2[j].z); yb[j][5] = w0 * bfhi(b0[j].z) + w1 * bfhi(b1[j].z) + w2 * bfhi(b2[j].z);
;         yb[j][6] = w0 * bflo(b0[j].w) + w1 * bflo(b1[j].w) + w2 * bflo(b2[j].w); yb[j][7] = w0 * bfhi(b0[j].w) + w1 * bfhi(b1[j].w) + w2 * bfhi(b2[j].w);
; #pragma unroll
;         for (int i = 0; i < 8; ++i) { ssa += ya[j][i] * ya[j][i]; ssb += yb[j][i] * yb[j][i]; } }
;     const float ra = 1.0f / sqrtf(wave_sum(ssa) * (1.0f / DA) + EPS), rb = 1.0f / sqrtf(wave_sum(ssb) * (1.0f / DB) + EPS);
; #pragma unroll
;     for (int j = 0; j < 2; ++j) { const int c = lane + 64 * j;
;         const float gaf[8] = {bflo(ga[j].x), bfhi(ga[j].x), bflo(ga[j].y), bfhi(ga[j].y), bflo(ga[j].z), bfhi(ga[j].z), bflo(ga[j].w), bfhi(ga[j].w)};
;         const float gbf[8] = {bflo(gb[j].x), bfhi(gb[j].x), bflo(gb[j].y), bfhi(gb[j].y), bflo(gb[j].z), bfhi(gb[j].z), bflo(gb[j].w), bfhi(gb[j].w)};
;         const f32x4 wa0 = *(const f32x4*)(wa + 8 * c), wa1 = *(const f32x4*)(wa + 8 * c + 4), wb0 = *(const f32x4*)(wb + 8 * c), wb1 = *(const f32x4*)(wb + 8 * c + 4);
;         float za[8], zb[8];
; #pragma unroll
;         for (int i = 0; i < 8; ++i) { const float wai = i < 4 ? wa0[i & 3] : wa1[i & 3], wbi = i < 4 ? wb0[i & 3] : wb1[i & 3];
;             const float sa = gaf[i] * __builtin_amdgcn_rcpf(1.0f + __builtin_amdgcn_exp2f(-1.4426950408889634f * gaf[i])), sb = gbf[i] * __builtin_amdgcn_rcpf(1.0f + __builtin_amdgcn_exp2f(-1.4426950408889634f * gbf[i]));
	v_lshlrev_b32_e32 v11, 16, v34
	s_waitcnt vmcnt(1)
	v_lshlrev_b32_e32 v10, 16, v38
	v_pk_mul_f32 v[10:11], v[2:3], v[10:11]
	v_fma_f32 v16, v80, v87, v21
	v_fma_f32 v11, v81, v93, v11
	v_add_f32_e32 v84, v10, v11
	v_and_b32_e32 v11, 0xffff0000, v34
	v_and_b32_e32 v10, 0xffff0000, v38
	v_pk_mul_f32 v[10:11], v[2:3], v[10:11]
	v_fma_f32 v13, v80, v86, v13
	v_fma_f32 v11, v81, v94, v11
	v_add_f32_e32 v85, v10, v11
	v_lshlrev_b32_e32 v11, 16, v35
	v_lshlrev_b32_e32 v10, 16, v39
	v_pk_mul_f32 v[10:11], v[2:3], v[10:11]
	v_fma_f32 v21, v80, v90, v47
	v_fma_f32 v11, v81, v95, v11
	v_add_f32_e32 v47, v20, v16
	v_add_f32_e32 v86, v10, v11
	v_and_b32_e32 v11, 0xffff0000, v35
	v_and_b32_e32 v10, 0xffff0000, v39
	v_fma_f32 v17, v80, v88, v43
	v_add_f32_e32 v45, v12, v13
	v_mul_f32_e32 v12, v47, v47
	v_pk_mul_f32 v[10:11], v[2:3], v[10:11]
	v_fma_f32 v43, v80, v91, v49
	v_add_f32_e32 v49, v42, v17
	v_fmac_f32_e32 v12, v45, v45
	v_fma_f32 v11, v81, v96, v11
	v_add_f32_e32 v77, v14, v15
	v_fmac_f32_e32 v12, v49, v49
	v_add_f32_e32 v87, v10, v11
	v_lshlrev_b32_e32 v11, 16, v36
	v_lshlrev_b32_e32 v10, 16, v40
	v_lshlrev_b32_e32 v97, 16, v4
	v_add_f32_e32 v79, v44, v19
	v_fmac_f32_e32 v12, v77, v77
	v_pk_mul_f32 v[10:11], v[2:3], v[10:11]
	v_add_f32_e32 v91, v46, v21
	v_fmac_f32_e32 v12, v79, v79
	v_fma_f32 v11, v81, v97, v11
	v_add_f32_e32 v98, v48, v43
	v_fmac_f32_e32 v12, v91, v91
	v_add_f32_e32 v88, v10, v11
	v_and_b32_e32 v11, 0xffff0000, v36
	v_and_b32_e32 v10, 0xffff0000, v40
	v_fmac_f32_e32 v12, v98, v98
	v_and_b32_e32 v4, 0xffff0000, v4
	v_pk_mul_f32 v[10:11], v[2:3], v[10:11]
	v_fmac_f32_e32 v12, v99, v99
	v_fma_f32 v4, v81, v4, v11
	v_add_f32_e32 v89, v10, v4
	v_lshlrev_b32_e32 v11, 16, v37
	v_lshlrev_b32_e32 v10, 16, v41
	v_fmac_f32_e32 v12, v84, v84
	v_lshlrev_b32_e32 v13, 16, v5
	v_pk_mul_f32 v[10:11], v[2:3], v[10:11]
	v_fmac_f32_e32 v12, v85, v85
	v_fma_f32 v4, v81, v13, v11
	v_fmac_f32_e32 v12, v86, v86
	v_add_f32_e32 v90, v10, v4
	v_and_b32_e32 v10, 0xffff0000, v5
	v_and_b32_e32 v5, 0xffff0000, v37
	v_and_b32_e32 v4, 0xffff0000, v41
	v_fmac_f32_e32 v12, v87, v87
	v_pk_mul_f32 v[2:3], v[2:3], v[4:5]
	v_fmac_f32_e32 v12, v88, v88
	global_load_dwordx4 v[40:43], v[60:61], off
	global_load_dwordx4 v[14:17], v[60:61], off offset:16
	v_fma_f32 v3, v81, v10, v3
	v_fmac_f32_e32 v12, v89, v89
	v_add_f32_e32 v82, v2, v3
	v_fmac_f32_e32 v12, v90, v90
	v_fmac_f32_e32 v12, v82, v82
	ds_bpermute_b32 v2, v140, v12
	v_and_b32_e32 v34, 0xffff0000, v25
	v_lshlrev_b32_e32 v35, 16, v25
	v_lshlrev_b32_e32 v44, 16, v26
	v_and_b32_e32 v46, 0xffff0000, v26
	s_waitcnt lgkmcnt(0)
	v_add_f32_e32 v2, v12, v2
	ds_bpermute_b32 v3, v141, v2
	v_lshlrev_b32_e32 v48, 16, v27
	v_and_b32_e32 v76, 0xffff0000, v27
	v_lshlrev_b32_e32 v78, 16, v28
	v_and_b32_e32 v80, 0xffff0000, v28
	s_waitcnt lgkmcnt(0)
	v_add_f32_e32 v2, v2, v3
	ds_bpermute_b32 v3, v142, v2
	v_mul_f32_e32 v37, 0xbfb8aa3b, v80
	v_exp_f32_e32 v37, v37
	v_lshlrev_b32_e32 v92, 16, v29
	v_pk_mul_f32 v[38:39], v[34:35], v[34:35]
	s_waitcnt lgkmcnt(0)
	v_add_f32_e32 v2, v2, v3
	ds_bpermute_b32 v3, v143, v2
	s_waitcnt lgkmcnt(0)
	v_add_f32_e32 v4, v2, v3
	ds_bpermute_b32 v5, v144, v4
	v_lshl_add_u64 v[2:3], s[44:45], 0, v[54:55]
	v_lshlrev_b64 v[2:3], 8, v[2:3]
	v_lshl_add_u64 v[2:3], v[50:51], 0, v[2:3]
	s_waitcnt lgkmcnt(0)
	v_add_f32_e32 v10, v4, v5
	ds_bpermute_b32 v11, v145, v10
	v_lshl_add_u64 v[4:5], s[44:45], 0, v[56:57]
	v_lshlrev_b64 v[4:5], 8, v[4:5]
	s_lshl_b64 s[44:45], s[44:45], 12
	s_waitcnt lgkmcnt(0)
	v_add_f32_e32 v10, v10, v11
	v_fmamk_f32 v10, v10, 0x3a800000, v215
	v_mul_f32_e32 v11, 0x4f800000, v10
	v_cmp_gt_f32_e32 vcc, s33, v10
	s_waitcnt vmcnt(1)
	v_mov_b32_e32 v95, v40
	v_cndmask_b32_e32 v18, v10, v11, vcc
	v_sqrt_f32_e32 v19, v18
	v_lshl_add_u64 v[10:11], v[50:51], 0, v[4:5]
	global_load_dwordx4 v[2:5], v[2:3], off
	s_nop 0
	global_load_dwordx4 v[10:13], v[10:11], off
	v_add_u32_e32 v20, -1, v19
	v_fma_f32 v21, -v20, v19, v18
	v_cmp_ge_f32_e64 s[0:1], 0, v21
	v_add_u32_e32 v21, 1, v19
	s_nop 0
	v_cndmask_b32_e64 v20, v19, v20, s[0:1]
	v_fma_f32 v19, -v21, v19, v18
	v_cmp_lt_f32_e64 s[0:1], 0, v19
	s_nop 1
	v_cndmask_b32_e64 v19, v20, v21, s[0:1]
	v_mul_f32_e32 v20, 0x37800000, v19
	v_cndmask_b32_e32 v19, v19, v20, vcc
	v_cmp_class_f32_e32 vcc, v18, v216
	s_nop 1
	v_cndmask_b32_e32 v18, v19, v18, vcc
	v_div_scale_f32 v19, s[0:1], v18, v18, 1.0
	v_rcp_f32_e32 v20, v19
	s_nop 0
	v_fma_f32 v21, -v19, v20, 1.0
	v_fmac_f32_e32 v20, v21, v20
	v_div_scale_f32 v21, vcc, 1.0, v18, 1.0
	v_mul_f32_e32 v25, v21, v20
	v_fma_f32 v36, -v19, v25, v21
	v_fmac_f32_e32 v25, v36, v20
	v_fma_f32 v19, -v19, v25, v21
	v_div_fmas_f32 v19, v19, v20, v25
	v_div_fixup_f32 v83, v19, v18, 1.0
	v_mul_f32_e32 v18, 0xbfb8aa3b, v44
	v_exp_f32_e32 v25, v18
	v_mul_f32_e32 v47, v47, v83
	v_mul_f32_e32 v49, v49, v83
	v_mul_f32_e32 v77, v77, v83
	v_add_f32_e32 v25, 1.0, v25
	v_rcp_f32_e32 v94, v25
	v_mul_f32_e32 v25, 0xbfb8aa3b, v46
	v_exp_f32_e32 v25, v25
	v_mul_f32_e32 v79, v79, v83
	v_mul_f32_e32 v81, v91, v83
	v_and_b32_e32 v36, 0xffff0000, v29
	v_add_f32_e32 v25, 1.0, v25
	v_rcp_f32_e32 v40, v25
	v_mul_f32_e32 v25, 0xbfb8aa3b, v48
	v_exp_f32_e32 v25, v25
	v_mul_f32_e32 v93, v98, v83
	v_pk_mul_f32 v[40:41], v[40:41], v[46:47]
	v_lshlrev_b32_e32 v46, 16, v8
	v_add_f32_e32 v25, 1.0, v25
	v_mul_f32_e32 v105, v40, v41
	v_rcp_f32_e32 v40, v25
	v_mul_f32_e32 v25, 0xbfb8aa3b, v76
	v_exp_f32_e32 v25, v25
	v_mov_b32_e32 v41, v42
	v_pk_mul_f32 v[40:41], v[40:41], v[48:49]
	v_mul_f32_e32 v45, v45, v83
	v_add_f32_e32 v25, 1.0, v25
	v_rcp_f32_e32 v42, v25
	v_mul_f32_e32 v25, 0xbfb8aa3b, v78
	v_exp_f32_e32 v25, v25
	v_mul_f32_e32 v106, v40, v41
	v_pk_mul_f32 v[40:41], v[42:43], v[76:77]
	v_pk_mul_f32 v[44:45], v[94:95], v[44:45]
	v_add_f32_e32 v25, 1.0, v25
	v_mul_f32_e32 v107, v40, v41
	v_rcp_f32_e32 v40, v25
	s_waitcnt vmcnt(2)
; __device__ __forceinline__ float bflo(unsigned w) { return __uint_as_float(w << 16); }
; __device__ __forceinline__ float bfhi(unsigned w) { return __uint_as_float(w & 0xffff0000u); }
; __device__ __forceinline__ void gate_row(int m, int lane, const bf16_t* __restrict__ YA, const bf16_t* __restrict__ YB, const float* __restrict__ LSE, const bf16_t* __restrict__ PROJ, ...
;     ...
;     const float ra = 1.0f / sqrtf(wave_sum(ssa) * (1.0f / DA) + EPS), rb = 1.0f / sqrtf(wave_sum(ssb) * (1.0f / DB) + EPS);
; #pragma unroll
;     for (int j = 0; j < 2; ++j) { const int c = lane + 64 * j;
;         const float gaf[8] = {bflo(ga[j].x), bfhi(ga[j].x), bflo(ga[j].y), bfhi(ga[j].y), bflo(ga[j].z), bfhi(ga[j].z), bflo(ga[j].w), bfhi(ga[j].w)};
;         const float gbf[8] = {bflo(gb[j].x), bfhi(gb[j].x), bflo(gb[j].y), bfhi(gb[j].y), bflo(gb[j].z), bfhi(gb[j].z), bflo(gb[j].w), bfhi(gb[j].w)};
;         const f32x4 wa0 = *(const f32x4*)(wa + 8 * c), wa1 = *(const f32x4*)(wa + 8 * c + 4), wb0 = *(const f32x4*)(wb + 8 * c), wb1 = *(const f32x4*)(wb + 8 * c + 4);
;         float za[8], zb[8];
; #pragma unroll
;         for (int i = 0; i < 8; ++i) { const float wai = i < 4 ? wa0[i & 3] : wa1[i & 3], wbi = i < 4 ? wb0[i & 3] : wb1[i & 3];
;             const float sa = gaf[i] * __builtin_amdgcn_rcpf(1.0f + __builtin_amdgcn_exp2f(-1.4426950408889634f * gaf[i])), sb = gbf[i] * __builtin_amdgcn_rcpf(1.0f + __builtin_amdgcn_exp2f(-1.4426950408889634f * gbf[i]));
;             za[i] = ya[j][i] * ra * wai * sa; zb[i] = yb[j][i] * rb * wbi * sb; }
	v_mov_b32_e32 v41, v14
	v_add_f32_e32 v14, 1.0, v37
	v_rcp_f32_e32 v14, v14
	v_pk_mul_f32 v[40:41], v[40:41], v[78:79]
	v_mul_f32_e32 v104, v44, v45
	v_mul_f32_e32 v108, v40, v41
	v_pk_mul_f32 v[14:15], v[14:15], v[80:81]
	v_lshlrev_b32_e32 v40, 16, v9
	v_mul_f32_e32 v91, v14, v15
	v_mul_f32_e32 v14, 0xbfb8aa3b, v92
	v_mul_f32_e32 v15, 0xbfb8aa3b, v40
	v_exp_f32_e32 v14, v14
	v_exp_f32_e32 v15, v15
	v_lshlrev_b32_e32 v41, 16, v33
	v_and_b32_e32 v45, 0xffff0000, v33
	v_add_f32_e32 v14, 1.0, v14
	v_add_f32_e32 v15, 1.0, v15
	v_rcp_f32_e32 v14, v14
	v_rcp_f32_e32 v42, v15
	v_mul_f32_e32 v15, 0xbfb8aa3b, v36
	v_exp_f32_e32 v25, v15
	v_mov_b32_e32 v15, v16
	v_pk_mul_f32 v[14:15], v[14:15], v[92:93]
	v_lshlrev_b32_e32 v93, 16, v30
	v_mul_f32_e32 v14, v14, v15
	v_add_f32_e32 v15, 1.0, v25
	v_rcp_f32_e32 v16, v15
	v_mul_f32_e32 v15, 0xbfb8aa3b, v46
	v_exp_f32_e32 v15, v15
	v_and_b32_e32 v44, 0xffff0000, v9
	v_lshlrev_b32_e32 v79, 16, v31
	v_and_b32_e32 v81, 0xffff0000, v31
	v_add_f32_e32 v9, 1.0, v15
	v_and_b32_e32 v95, 0xffff0000, v30
	v_lshlrev_b32_e32 v15, 16, v23
	v_and_b32_e32 v31, 0xffff0000, v23
	v_lshlrev_b32_e32 v23, 16, v22
	v_and_b32_e32 v33, 0xffff0000, v22
	v_mul_f32_e32 v22, v93, v93
	v_fmac_f32_e32 v22, v95, v95
	global_load_dwordx4 v[18:21], v[58:59], off offset:16
	global_load_dwordx4 v[26:29], v[58:59], off
	v_fmac_f32_e32 v22, v79, v79
	v_lshlrev_b32_e32 v47, 16, v32
	v_fmac_f32_e32 v22, v81, v81
	v_and_b32_e32 v49, 0xffff0000, v32
	v_fmac_f32_e32 v22, v47, v47
	v_fmac_f32_e32 v22, v49, v49
	v_fmac_f32_e32 v22, v41, v41
	v_fmac_f32_e32 v22, v45, v45
	v_fmac_f32_e32 v22, v23, v23
	v_fmac_f32_e32 v22, v33, v33
	v_fmac_f32_e32 v22, v15, v15
	v_rcp_f32_e32 v76, v9
	v_lshlrev_b32_e32 v9, 16, v24
	v_fmac_f32_e32 v22, v31, v31
	v_and_b32_e32 v25, 0xffff0000, v24
	v_fmac_f32_e32 v22, v9, v9
	v_fmac_f32_e32 v22, v25, v25
	v_add_f32_e32 v22, v39, v22
	v_add_f32_e32 v22, v38, v22
	ds_bpermute_b32 v24, v140, v22
	v_and_b32_e32 v48, 0xffff0000, v8
	v_mul_f32_e32 v8, 0xbfb8aa3b, v48
	v_lshlrev_b32_e32 v78, 16, v7
	v_exp_f32_e32 v8, v8
	s_waitcnt lgkmcnt(0)
	v_add_f32_e32 v22, v22, v24
	ds_bpermute_b32 v24, v141, v22
	v_mul_f32_e32 v30, 0xbfb8aa3b, v78
	v_exp_f32_e32 v30, v30
	v_add_f32_e32 v8, 1.0, v8
	v_and_b32_e32 v80, 0xffff0000, v7
	s_waitcnt lgkmcnt(0)
	v_add_f32_e32 v22, v22, v24
	ds_bpermute_b32 v24, v142, v22
	v_rcp_f32_e32 v38, v8
	v_add_f32_e32 v8, 1.0, v30
	v_mul_f32_e32 v7, 0xbfb8aa3b, v80
	v_lshlrev_b32_e32 v92, 16, v6
	s_waitcnt lgkmcnt(0)
	v_add_f32_e32 v22, v22, v24
	ds_bpermute_b32 v24, v143, v22
	v_exp_f32_e32 v7, v7
	v_mul_f32_e32 v30, 0xbfb8aa3b, v92
	v_rcp_f32_e32 v96, v8
	v_exp_f32_e32 v30, v30
	s_waitcnt lgkmcnt(0)
	v_add_f32_e32 v8, v22, v24
	ds_bpermute_b32 v22, v144, v8
	v_add_f32_e32 v7, 1.0, v7
	v_and_b32_e32 v94, 0xffff0000, v6
	v_rcp_f32_e32 v98, v7
	v_add_f32_e32 v7, 1.0, v30
	v_mul_f32_e32 v6, 0xbfb8aa3b, v94
	v_exp_f32_e32 v24, v6
	v_rcp_f32_e32 v6, v7
	s_waitcnt lgkmcnt(0)
	v_add_f32_e32 v7, v8, v22
	ds_bpermute_b32 v8, v145, v7
	v_add_f32_e32 v22, 1.0, v24
	v_rcp_f32_e32 v100, v22
	v_mul_f32_e32 v22, 0xbfb8aa3b, v44
	v_exp_f32_e32 v22, v22
	s_waitcnt lgkmcnt(0)
	v_add_f32_e32 v7, v7, v8
	v_fmamk_f32 v7, v7, 0x3a800000, v215
	v_mul_f32_e32 v8, 0x4f800000, v7
	v_cmp_gt_f32_e32 vcc, s33, v7
	v_add_f32_e32 v22, 1.0, v22
	v_rcp_f32_e32 v102, v22
	v_cndmask_b32_e32 v7, v7, v8, vcc
	v_sqrt_f32_e32 v8, v7
	v_mul_f32_e32 v37, v99, v83
	v_pk_mul_f32 v[16:17], v[16:17], v[36:37]
	v_mul_f32_e32 v109, v85, v83
	v_add_u32_e32 v22, -1, v8
	v_fma_f32 v24, -v22, v8, v7
	v_cmp_ge_f32_e64 s[0:1], 0, v24
	v_add_u32_e32 v24, 1, v8
	v_mul_f32_e32 v111, v84, v83
	v_cndmask_b32_e64 v22, v8, v22, s[0:1]
	v_fma_f32 v8, -v24, v8, v7
	v_cmp_lt_f32_e64 s[0:1], 0, v8
	s_nop 1
	v_cndmask_b32_e64 v8, v22, v24, s[0:1]
	v_mul_f32_e32 v22, 0x37800000, v8
	v_cndmask_b32_e32 v8, v8, v22, vcc
	v_cmp_class_f32_e32 vcc, v7, v216
	v_mul_f32_e32 v24, v16, v17
	v_lshl_add_u64 v[16:17], v[62:63], 0, s[44:45]
	v_cndmask_b32_e32 v7, v8, v7, vcc
	v_div_scale_f32 v8, s[0:1], v7, v7, 1.0
	v_rcp_f32_e32 v22, v8
	s_nop 0
	v_fma_f32 v30, -v8, v22, 1.0
	v_fmac_f32_e32 v22, v30, v22
	v_div_scale_f32 v30, vcc, 1.0, v7, 1.0
	v_mul_f32_e32 v32, v30, v22
	v_fma_f32 v36, -v8, v32, v30
	v_fmac_f32_e32 v32, v36, v22
	v_fma_f32 v8, -v8, v32, v30
	v_div_fmas_f32 v8, v8, v22, v32
	v_div_fixup_f32 v7, v8, v7, 1.0
	v_pk_mul_f32 v[36:37], v[6:7], v[92:93]
	v_mov_b32_e32 v101, v7
	s_waitcnt vmcnt(0)
; __device__ __forceinline__ unsigned pk2(float lo, float hi) { unsigned r; asm("v_cvt_pk_bf16_f32 %0, %1, %2" : "=v"(r) : "v"(lo), "v"(hi)); return r; }
; __device__ __forceinline__ float bflo(unsigned w) { return __uint_as_float(w << 16); }
; __device__ __forceinline__ float bfhi(unsigned w) { return __uint_as_float(w & 0xffff0000u); }
; __device__ __forceinline__ void gate_row(int m, int lane, const bf16_t* __restrict__ YA, const bf16_t* __restrict__ YB, const float* __restrict__ LSE, const bf16_t* __restrict__ PROJ, ...
;     ...
;     for (int j = 0; j < 2; ++j) { const int c = lane + 64 * j;
;         const float gaf[8] = {bflo(ga[j].x), bfhi(ga[j].x), bflo(ga[j].y), bfhi(ga[j].y), bflo(ga[j].z), bfhi(ga[j].z), bflo(ga[j].w), bfhi(ga[j].w)};
;         const float gbf[8] = {bflo(gb[j].x), bfhi(gb[j].x), bflo(gb[j].y), bfhi(gb[j].y), bflo(gb[j].z), bfhi(gb[j].z), bflo(gb[j].w), bfhi(gb[j].w)};
;         const f32x4 wa0 = *(const f32x4*)(wa + 8 * c), wa1 = *(const f32x4*)(wa + 8 * c + 4), wb0 = *(const f32x4*)(wb + 8 * c), wb1 = *(const f32x4*)(wb + 8 * c + 4);
;         float za[8], zb[8];
; #pragma unroll
;         for (int i = 0; i < 8; ++i) { const float wai = i < 4 ? wa0[i & 3] : wa1[i & 3], wbi = i < 4 ? wb0[i & 3] : wb1[i & 3];
;             const float sa = gaf[i] * __builtin_amdgcn_rcpf(1.0f + __builtin_amdgcn_exp2f(-1.4426950408889634f * gaf[i])), sb = gbf[i] * __builtin_amdgcn_rcpf(1.0f + __builtin_amdgcn_exp2f(-1.4426950408889634f * gbf[i]));
;             za[i] = ya[j][i] * ra * wai * sa; zb[i] = yb[j][i] * rb * wbi * sb; }
;         v4u oa, ob; oa.x = pk2(za[0], za[1]); oa.y = pk2(za[2], za[3]); oa.z = pk2(za[4], za[5]); oa.w = pk2(za[6], za[7]);
;         ob.x = pk2(zb[0], zb[1]); ob.y = pk2(zb[2], zb[3]); ob.z = pk2(zb[4], zb[5]); ob.w = pk2(zb[6], zb[7]);
;         *(v4u*)(H + (size_t)m * DM + 8 * c) = oa; *(v4u*)(H + (size_t)m * DM + DA + 8 * c) = ob; }
	v_mul_f32_e32 v6, v26, v37
	v_mul_f32_e32 v6, v36, v6
	v_pk_mul_f32 v[36:37], v[100:101], v[94:95]
	v_mov_b32_e32 v97, v7
	v_mul_f32_e32 v8, v27, v37
	v_pk_mul_f32 v[26:27], v[96:97], v[78:79]
	v_mov_b32_e32 v99, v7
	v_mul_f32_e32 v22, v28, v27
	v_mul_f32_e32 v22, v26, v22
	v_pk_mul_f32 v[26:27], v[98:99], v[80:81]
	v_mov_b32_e32 v77, v7
	v_mul_f32_e32 v27, v29, v27
	v_mul_f32_e32 v28, v26, v27
	v_pk_mul_f32 v[26:27], v[76:77], v[46:47]
	v_mov_b32_e32 v39, v7
	v_mul_f32_e32 v18, v18, v27
	v_mul_f32_e32 v29, v26, v18
	v_pk_mul_f32 v[26:27], v[38:39], v[48:49]
	v_mov_b32_e32 v43, v7
	v_mul_f32_e32 v18, v19, v27
	v_mul_f32_e32 v26, v26, v18
	v_pk_mul_f32 v[18:19], v[42:43], v[40:41]
	v_mov_b32_e32 v103, v7
	v_mul_f32_e32 v19, v20, v19
	v_mul_f32_e32 v27, v18, v19
	v_pk_mul_f32 v[18:19], v[102:103], v[44:45]
	v_mul_f32_e32 v8, v36, v8
	v_mul_f32_e32 v19, v21, v19
	v_mul_f32_e32 v21, v18, v19
	v_cvt_pk_bf16_f32 v18, v6, v8
	v_cvt_pk_bf16_f32 v19, v22, v28
	v_cvt_pk_bf16_f32 v20, v29, v26
	v_cvt_pk_bf16_f32 v21, v27, v21
	v_cvt_pk_bf16_f32 v26, v104, v105
	v_cvt_pk_bf16_f32 v27, v106, v107
	v_cvt_pk_bf16_f32 v28, v108, v91
	v_cvt_pk_bf16_f32 v29, v14, v24
	global_store_dwordx4 v[16:17], v[18:21], off
	global_store_dwordx4 v[16:17], v[26:29], off offset:2048
	global_load_dwordx4 v[18:21], v[60:61], off offset:2064
	v_lshlrev_b32_e32 v40, 16, v13
	global_load_dwordx4 v[26:29], v[58:59], off offset:2064
	global_load_dwordx4 v[36:39], v[58:59], off offset:2048
	v_mul_f32_e32 v45, v90, v83
	v_lshlrev_b32_e32 v48, 16, v10
	v_and_b32_e32 v76, 0xffff0000, v10
	v_lshlrev_b32_e32 v78, 16, v11
	v_and_b32_e32 v80, 0xffff0000, v11
	v_lshlrev_b32_e32 v90, 16, v12
	v_and_b32_e32 v92, 0xffff0000, v12
	v_and_b32_e32 v94, 0xffff0000, v13
	global_load_dwordx4 v[10:13], v[60:61], off offset:2048
	v_mul_f32_e32 v6, 0xbfb8aa3b, v40
	v_lshlrev_b32_e32 v42, 16, v5
	v_exp_f32_e32 v6, v6
	v_mul_f32_e32 v8, 0xbfb8aa3b, v42
	v_exp_f32_e32 v8, v8
	v_and_b32_e32 v96, 0xffff0000, v5
	v_add_f32_e32 v6, 1.0, v6
	v_rcp_f32_e32 v44, v6
	v_add_f32_e32 v6, 1.0, v8
	v_mul_f32_e32 v5, 0xbfb8aa3b, v92
	v_rcp_f32_e32 v46, v6
	v_exp_f32_e32 v5, v5
	v_mul_f32_e32 v6, 0xbfb8aa3b, v90
	v_exp_f32_e32 v6, v6
	v_lshlrev_b32_e32 v8, 16, v4
	v_add_f32_e32 v5, 1.0, v5
	v_rcp_f32_e32 v98, v5
	v_add_f32_e32 v5, 1.0, v6
	v_rcp_f32_e32 v100, v5
	v_mul_f32_e32 v5, 0xbfb8aa3b, v8
	v_exp_f32_e32 v5, v5
	v_mul_f32_e32 v101, v88, v83
	v_and_b32_e32 v30, 0xffff0000, v3
	v_lshlrev_b32_e32 v14, 16, v3
	v_add_f32_e32 v5, 1.0, v5
	v_rcp_f32_e32 v88, v5
	v_mul_f32_e32 v5, 0xbfb8aa3b, v78
	v_exp_f32_e32 v5, v5
	v_mul_f32_e32 v3, 0xbfb8aa3b, v30
	v_exp_f32_e32 v3, v3
	v_mul_f32_e32 v105, v86, v83
	v_add_f32_e32 v5, 1.0, v5
	v_rcp_f32_e32 v104, v5
	v_mul_f32_e32 v5, 0xbfb8aa3b, v14
	v_exp_f32_e32 v5, v5
	v_add_f32_e32 v3, 1.0, v3
	v_rcp_f32_e32 v86, v3
	v_and_b32_e32 v24, 0xffff0000, v4
	v_add_f32_e32 v3, 1.0, v5
	v_mul_f32_e32 v5, 0xbfb8aa3b, v76
	v_exp_f32_e32 v5, v5
	v_mul_f32_e32 v4, 0xbfb8aa3b, v24
	v_exp_f32_e32 v4, v4
	v_and_b32_e32 v32, 0xffff0000, v2
	v_add_f32_e32 v5, 1.0, v5
	v_rcp_f32_e32 v108, v5
	v_mul_f32_e32 v5, 0xbfb8aa3b, v32
	v_add_f32_e32 v4, 1.0, v4
	v_mul_f32_e32 v6, 0xbfb8aa3b, v80
	v_rcp_f32_e32 v106, v3
	v_mul_f32_e32 v3, 0xbfb8aa3b, v48
	v_exp_f32_e32 v5, v5
	v_rcp_f32_e32 v4, v4
	v_exp_f32_e32 v6, v6
	v_exp_f32_e32 v3, v3
	v_lshlrev_b32_e32 v22, 16, v2
	v_add_f32_e32 v2, 1.0, v5
	v_mov_b32_e32 v5, v7
	v_add_f32_e32 v6, 1.0, v6
	v_add_f32_e32 v3, 1.0, v3
	v_pk_mul_f32 v[4:5], v[4:5], v[24:25]
	v_rcp_f32_e32 v102, v6
	v_rcp_f32_e32 v110, v3
	v_mul_f32_e32 v99, v89, v83
	v_mov_b32_e32 v89, v7
	v_mul_f32_e32 v103, v87, v83
	v_mov_b32_e32 v87, v7
	s_waitcnt vmcnt(3)
	v_mov_b32_e32 v91, v18
	v_mov_b32_e32 v107, v7
	s_waitcnt vmcnt(2)
	v_mul_f32_e32 v3, v5, v27
	v_mul_f32_e32 v24, v4, v3
	v_pk_mul_f32 v[4:5], v[100:101], v[90:91]
	v_rcp_f32_e32 v2, v2
	v_mul_f32_e32 v18, v4, v5
	v_pk_mul_f32 v[4:5], v[88:89], v[8:9]
	v_mov_b32_e32 v41, v20
	v_mul_f32_e32 v3, v5, v26
	v_mul_f32_e32 v8, v4, v3
	v_mov_b32_e32 v97, v29
	s_waitcnt vmcnt(0)
	v_mov_b32_e32 v81, v13
	v_pk_mul_f32 v[4:5], v[102:103], v[80:81]
	v_mov_b32_e32 v79, v12
	v_mul_f32_e32 v9, v4, v5
	v_pk_mul_f32 v[4:5], v[86:87], v[30:31]
	v_mov_b32_e32 v77, v11
	v_mul_f32_e32 v3, v5, v39
	v_mul_f32_e32 v13, v4, v3
	v_pk_mul_f32 v[4:5], v[104:105], v[78:79]
	v_mov_b32_e32 v49, v10
	v_mul_f32_e32 v12, v4, v5
	v_pk_mul_f32 v[4:5], v[106:107], v[14:15]
	v_pk_mul_f32 v[40:41], v[44:45], v[40:41]
	v_mul_f32_e32 v3, v5, v38
	v_mul_f32_e32 v14, v4, v3
	v_pk_mul_f32 v[4:5], v[108:109], v[76:77]
	v_mov_b32_e32 v3, v7
	v_mul_f32_e32 v11, v4, v5
	v_mul_f32_e32 v4, 0xbfb8aa3b, v22
	v_exp_f32_e32 v4, v4
	v_pk_mul_f32 v[2:3], v[2:3], v[32:33]
	v_mul_f32_e32 v5, 0xbfb8aa3b, v94
	v_mul_f32_e32 v3, v3, v37
	v_mul_f32_e32 v15, v2, v3
	v_add_f32_e32 v2, 1.0, v4
	v_rcp_f32_e32 v6, v2
	v_mul_f32_e32 v4, 0xbfb8aa3b, v96
	v_exp_f32_e32 v4, v4
	v_pk_mul_f32 v[2:3], v[110:111], v[48:49]
	v_exp_f32_e32 v5, v5
	v_mul_f32_e32 v10, v2, v3
	v_pk_mul_f32 v[2:3], v[6:7], v[22:23]
	v_mul_f32_e32 v47, v7, v35
	v_mul_f32_e32 v3, v3, v36
	v_mul_f32_e32 v6, v2, v3
	v_add_f32_e32 v2, 1.0, v4
	v_rcp_f32_e32 v2, v2
	v_add_f32_e32 v3, 1.0, v5
	v_rcp_f32_e32 v4, v3
	v_mul_f32_e32 v3, v7, v34
	v_mov_b32_e32 v43, v28
	v_pk_mul_f32 v[2:3], v[2:3], v[96:97]
	v_mul_f32_e32 v5, v82, v83
	v_mov_b32_e32 v95, v21
	v_mul_f32_e32 v20, v40, v41
	v_pk_mul_f32 v[40:41], v[46:47], v[42:43]
	v_mov_b32_e32 v93, v19
	v_mul_f32_e32 v7, v2, v3
	v_pk_mul_f32 v[2:3], v[4:5], v[94:95]
	v_mul_f32_e32 v28, v40, v41
	v_pk_mul_f32 v[40:41], v[98:99], v[92:93]
	v_mul_f32_e32 v21, v2, v3
	v_cvt_pk_bf16_f32 v2, v6, v15
	v_cvt_pk_bf16_f32 v3, v14, v13
	v_cvt_pk_bf16_f32 v4, v8, v24
	v_cvt_pk_bf16_f32 v5, v28, v7
	v_mul_f32_e32 v19, v40, v41
	v_cvt_pk_bf16_f32 v6, v10, v11
	v_cvt_pk_bf16_f32 v7, v12, v9
	v_cvt_pk_bf16_f32 v8, v18, v19
	v_cvt_pk_bf16_f32 v9, v20, v21
	global_store_dwordx4 v[16:17], v[2:5], off offset:1024
	global_store_dwordx4 v[16:17], v[6:9], off offset:3072
	s_branch .LBB0_40
